# P13 pool + P14 sgu head-barrier sinking with deferred wave-0 vector loads; P15 sgu tail loads batched; P16 pool slab loads before weights with counted wait
# baseline (speedup 1.0000x reference)
.LBB0_306:
	v_mov_b32_e32 v110, v204
	s_and_b32 s29, s39, 3
	s_lshl_b32 s28, s29, 8
	v_cmp_gt_i32_e32 vcc, 64, v110
	s_and_saveexec_b64 s[0:1], vcc
	s_cbranch_execz .LBB0_308
	s_lshl_b32 s40, s28, 2
	s_add_u32 s40, s22, s40
	v_lshlrev_b32_e32 v2, 2, v110
	s_addc_u32 s41, s23, 0
	v_ashrrev_i32_e32 v3, 31, v2
	v_lshl_add_u64 v[2:3], v[2:3], 2, s[40:41]
	global_load_dwordx4 v[206:209], v[2:3], off
	v_lshl_add_u32 v210, v110, 4, 0
	v_add_u32_e32 v210, 0x11000, v210
.LBB0_308:
	s_or_b64 exec, exec, s[0:1]
	s_lshl_b32 s0, s39, 5
	s_and_b32 s40, s0, 0xffffff80
	s_or_b32 s0, s29, s38
	s_lshl_b32 s1, s0, 15
	s_add_u32 s44, s30, s1
	v_lshlrev_b32_e32 v0, 4, v110
	s_addc_u32 s45, s31, 0
	v_and_b32_e32 v0, 0x3f0, v0
	v_ashrrev_i32_e32 v84, 2, v110
	v_lshl_add_u64 v[106:107], s[44:45], 0, v[0:1]
	global_load_dwordx4 v[2:5], v0, s[44:45]
	global_load_dwordx4 v[26:29], v0, s[44:45] offset:1024
	global_load_dwordx4 v[22:25], v0, s[44:45] offset:2048
	global_load_dwordx4 v[18:21], v0, s[44:45] offset:3072
	v_add_u32_e32 v0, s40, v84
	v_mov_b64_e32 v[6:7], s[24:25]
	v_mad_i64_i32 v[6:7], s[44:45], v0, s77, v[6:7]
	v_lshlrev_b32_e32 v0, 6, v110
	s_lshl_b32 s60, s28, 1
	v_and_b32_e32 v85, 0xc0, v0
	v_lshl_add_u64 v[6:7], v[6:7], 0, s[60:61]
	v_lshlrev_b32_e32 v0, 1, v85
	v_lshl_add_u64 v[6:7], v[6:7], 0, v[0:1]
	s_mov_b64 s[44:45], 0x1800
	v_lshl_add_u64 v[30:31], v[6:7], 0, s[44:45]
	global_load_dwordx4 v[74:77], v[30:31], off offset:32
	global_load_dwordx4 v[86:89], v[30:31], off offset:80
	v_add_co_u32_e32 v6, vcc, s46, v6
	v_and_b32_e32 v10, 64, v201
	s_nop 0
	v_addc_co_u32_e32 v7, vcc, 0, v7, vcc
	global_load_dwordx4 v[90:93], v[6:7], off offset:2048
	s_nop 0
	global_load_dwordx4 v[6:9], v[30:31], off offset:64
	global_load_dwordx4 v[70:73], v[30:31], off offset:48
	v_add_u32_e32 v116, 64, v10
	global_load_dwordx4 v[14:17], v[30:31], off offset:96
	global_load_dwordx4 v[10:13], v[30:31], off offset:112
	global_load_dwordx4 v[94:97], v[30:31], off offset:16
	v_add_co_u32_e32 v34, vcc, s46, v106
	s_movk_i32 s1, 0x3000
	s_nop 0
	v_addc_co_u32_e32 v35, vcc, 0, v107, vcc
	v_add_co_u32_e32 v36, vcc, s34, v106
	v_xor_b32_e32 v111, 1, v201
	s_nop 0
	v_addc_co_u32_e32 v37, vcc, 0, v107, vcc
	v_add_co_u32_e32 v78, vcc, s1, v106
	s_movk_i32 s1, 0x4000
	s_nop 0
	v_addc_co_u32_e32 v79, vcc, 0, v107, vcc
	v_add_co_u32_e32 v108, vcc, s1, v106
	s_movk_i32 s1, 0x208
	s_nop 0
	v_addc_co_u32_e32 v109, vcc, 0, v107, vcc
	v_cmp_lt_i32_e32 vcc, v111, v116
	global_load_dwordx4 v[62:65], v[34:35], off offset:1024
	global_load_dwordx4 v[54:57], v[34:35], off offset:2048
	global_load_dwordx4 v[66:69], v[36:37], off offset:-4096
	global_load_dwordx4 v[30:33], v[36:37], off
	global_load_dwordx4 v[50:53], v[36:37], off offset:1024
	global_load_dwordx4 v[46:49], v[36:37], off offset:2048
	global_load_dwordx4 v[42:45], v[36:37], off offset:3072
	global_load_dwordx4 v[38:41], v[108:109], off offset:-4096
	global_load_dwordx4 v[58:61], v[34:35], off offset:3072
	s_nop 0
	global_load_dwordx4 v[34:37], v[78:79], off offset:1024
	s_waitcnt vmcnt(0)
	v_lshlrev_b32_e32 v81, 16, v75
	v_lshlrev_b32_e32 v80, 16, v74
	v_and_b32_e32 v99, 0xffff0000, v75
	v_and_b32_e32 v98, 0xffff0000, v74
	v_lshlrev_b32_e32 v75, 16, v87
	v_lshlrev_b32_e32 v74, 16, v86
	v_and_b32_e32 v87, 0xffff0000, v87
	v_and_b32_e32 v86, 0xffff0000, v86
	v_lshlrev_b32_e32 v83, 16, v77
	v_lshlrev_b32_e32 v82, 16, v76
	v_and_b32_e32 v101, 0xffff0000, v77
	v_and_b32_e32 v100, 0xffff0000, v76
	v_lshlrev_b32_e32 v77, 16, v89
	v_lshlrev_b32_e32 v76, 16, v88
	v_and_b32_e32 v89, 0xffff0000, v89
	v_and_b32_e32 v88, 0xffff0000, v88
	v_pk_add_f32 v[102:103], v[80:81], v[98:99]
	v_pk_add_f32 v[112:113], v[74:75], v[86:87]
	v_pk_add_f32 v[104:105], v[82:83], v[100:101]
	v_pk_add_f32 v[114:115], v[76:77], v[88:89]
	v_pk_add_f32 v[102:103], v[102:103], v[102:103] op_sel:[0,1] op_sel_hi:[1,0]
	v_pk_add_f32 v[112:113], v[112:113], v[112:113] op_sel:[0,1] op_sel_hi:[1,0]
	v_pk_add_f32 v[102:103], v[104:105], v[102:103]
	v_pk_add_f32 v[112:113], v[114:115], v[112:113]
	v_pk_add_f32 v[102:103], v[104:105], v[102:103] op_sel:[1,0] op_sel_hi:[0,1]
	v_pk_add_f32 v[104:105], v[114:115], v[112:113] op_sel:[1,0] op_sel_hi:[0,1]
	v_lshlrev_b32_e32 v112, 16, v93
	v_and_b32_e32 v113, 0xffff0000, v93
	v_pk_mov_b32 v[132:133], v[16:17], v[12:13] op_sel:[1,0]
	v_lshlrev_b32_e32 v135, 16, v12
	v_and_b32_e32 v136, 0xffff0000, v13
	v_lshlrev_b32_e32 v137, 16, v13
	v_lshlrev_b32_e32 v12, 16, v97
	v_and_b32_e32 v13, 0xffff0000, v97
	v_mov_b32_e32 v140, v112
	v_mov_b32_e32 v141, v12
	v_mov_b32_e32 v142, v113
	v_mov_b32_e32 v143, v13
	v_lshlrev_b32_e32 v114, 16, v92
	v_and_b32_e32 v115, 0xffff0000, v92
	v_pk_add_f32 v[140:141], v[140:141], v[142:143]
	v_lshlrev_b32_e32 v142, 16, v96
	v_and_b32_e32 v143, 0xffff0000, v96
	v_mov_b32_e32 v96, v114
	v_mov_b32_e32 v97, v142
	v_mov_b32_e32 v144, v115
	v_mov_b32_e32 v145, v143
	v_cndmask_b32_e32 v103, v201, v111, vcc
	v_lshlrev_b32_e32 v92, 16, v91
	v_and_b32_e32 v93, 0xffff0000, v91
	v_pk_add_f32 v[96:97], v[96:97], v[144:145]
	v_lshlrev_b32_e32 v144, 16, v95
	v_and_b32_e32 v145, 0xffff0000, v95
	v_lshlrev_b32_e32 v111, 2, v103
	v_xor_b32_e32 v103, 2, v201
	v_mov_b32_e32 v146, v92
	v_mov_b32_e32 v147, v144
	v_mov_b32_e32 v148, v93
	v_mov_b32_e32 v149, v145
	v_cmp_lt_i32_e32 vcc, v103, v116
	v_lshlrev_b32_e32 v116, 16, v90
	v_and_b32_e32 v117, 0xffff0000, v90
	v_pk_add_f32 v[146:147], v[146:147], v[148:149]
	v_lshlrev_b32_e32 v148, 16, v94
	v_and_b32_e32 v149, 0xffff0000, v94
	v_mov_b32_e32 v94, v116
	v_mov_b32_e32 v95, v148
	v_mov_b32_e32 v150, v117
	v_mov_b32_e32 v151, v149
	v_pk_add_f32 v[94:95], v[94:95], v[150:151]
	v_lshlrev_b32_e32 v91, 16, v6
	v_pk_add_f32 v[94:95], v[94:95], v[146:147]
	v_and_b32_e32 v119, 0xffff0000, v6
	v_pk_add_f32 v[94:95], v[96:97], v[94:95]
	v_lshlrev_b32_e32 v150, 16, v70
	v_pk_add_f32 v[94:95], v[140:141], v[94:95]
	v_lshlrev_b32_e32 v140, 16, v71
	v_add_f32_e32 v6, 0, v94
	v_and_b32_e32 v141, 0xffff0000, v71
	v_and_b32_e32 v151, 0xffff0000, v70
	v_pk_mov_b32 v[122:123], v[72:73], v[8:9] op_sel:[1,0]
	v_lshlrev_b32_e32 v125, 16, v8
	v_add_f32_e32 v8, v6, v95
	v_pk_add_f32 v[146:147], v[140:141], v[140:141] op_sel:[1,0] op_sel_hi:[0,1]
	v_pk_add_f32 v[70:71], v[150:151], v[150:151] op_sel:[1,0] op_sel_hi:[0,1]
	v_lshlrev_b32_e32 v6, 16, v7
	v_and_b32_e32 v7, 0xffff0000, v7
	v_lshlrev_b32_e32 v90, 16, v72
	v_and_b32_e32 v118, 0xffff0000, v72
	v_mov_b32_e32 v147, v7
	v_mov_b32_e32 v71, v6
	v_cndmask_b32_e32 v103, v201, v103, vcc
	v_pk_add_f32 v[120:121], v[90:91], v[118:119]
	v_lshlrev_b32_e32 v124, 16, v73
	v_and_b32_e32 v73, 0xffff0000, v123
	v_and_b32_e32 v72, 0xffff0000, v122
	v_lshlrev_b32_e32 v152, 16, v9
	v_and_b32_e32 v153, 0xffff0000, v9
	v_pk_add_f32 v[70:71], v[70:71], v[146:147]
	v_lshlrev_b32_e32 v198, 2, v103
	v_pk_add_f32 v[122:123], v[124:125], v[72:73]
	v_mov_b32_e32 v103, v153
	v_mov_b32_e32 v9, v152
	v_pk_add_f32 v[70:71], v[120:121], v[70:71]
	v_pk_add_f32 v[8:9], v[8:9], v[102:103]
	v_pk_add_f32 v[70:71], v[122:123], v[70:71]
	v_mov_b32_e32 v105, v136
	v_pk_add_f32 v[8:9], v[8:9], v[70:71]
	v_mov_b32_e32 v94, v83
	v_pk_add_f32 v[8:9], v[8:9], v[8:9] op_sel:[0,1] op_sel_hi:[1,0]
	v_mov_b32_e32 v95, v101
	v_mov_b32_e32 v9, v137
	v_mov_b32_e32 v83, v100
	v_mov_b32_e32 v100, v90
	v_mov_b32_e32 v101, v118
	v_pk_add_f32 v[8:9], v[8:9], v[104:105]
	v_mov_b32_e32 v118, v91
	v_lshlrev_b32_e32 v90, 16, v15
	v_and_b32_e32 v91, 0xffff0000, v15
	v_lshlrev_b32_e32 v104, 16, v14
	v_and_b32_e32 v105, 0xffff0000, v14
	v_lshlrev_b32_e32 v127, 16, v10
	v_and_b32_e32 v129, 0xffff0000, v10
	v_pk_add_f32 v[102:103], v[90:91], v[90:91] op_sel:[1,0] op_sel_hi:[0,1]
	v_pk_add_f32 v[14:15], v[104:105], v[104:105] op_sel:[1,0] op_sel_hi:[0,1]
	v_lshlrev_b32_e32 v10, 16, v11
	v_and_b32_e32 v11, 0xffff0000, v11
	v_lshlrev_b32_e32 v126, 16, v16
	v_and_b32_e32 v128, 0xffff0000, v16
	v_mov_b32_e32 v103, v11
	v_mov_b32_e32 v15, v10
	v_pk_add_f32 v[130:131], v[126:127], v[128:129]
	v_lshlrev_b32_e32 v134, 16, v17
	v_and_b32_e32 v17, 0xffff0000, v133
	v_and_b32_e32 v16, 0xffff0000, v132
	v_pk_add_f32 v[14:15], v[14:15], v[102:103]
	v_pk_add_f32 v[132:133], v[134:135], v[16:17]
	v_pk_add_f32 v[14:15], v[130:131], v[14:15]
	v_mov_b32_e32 v70, v77
	v_pk_add_f32 v[14:15], v[132:133], v[14:15]
	v_mov_b32_e32 v77, v88
	v_pk_add_f32 v[8:9], v[8:9], v[14:15]
	v_mov_b32_e32 v88, v75
	v_add_f32_e32 v8, v8, v9
	ds_bpermute_b32 v9, v111, v8
	v_mov_b32_e32 v75, v86
	v_mov_b32_e32 v96, v81
	v_mov_b32_e32 v97, v99
	v_mov_b32_e32 v81, v98
	s_waitcnt lgkmcnt(0)
	v_add_f32_e32 v8, v8, v9
	ds_bpermute_b32 v9, v198, v8
	v_mov_b32_e32 v98, v124
	v_mov_b32_e32 v99, v72
	v_mov_b32_e32 v72, v125
	v_mov_b32_e32 v71, v89
	s_waitcnt lgkmcnt(0)
	v_add_f32_e32 v8, v8, v9
	v_mul_f32_e32 v86, 0x3b800000, v8
	v_pk_add_f32 v[102:103], v[116:117], v[86:87] op_sel_hi:[1,0] neg_lo:[0,1] neg_hi:[0,1]
	v_pk_add_f32 v[92:93], v[92:93], v[86:87] op_sel_hi:[1,0] neg_lo:[0,1] neg_hi:[0,1]
	v_pk_mul_f32 v[116:117], v[102:103], v[102:103]
	v_pk_mul_f32 v[120:121], v[92:93], v[92:93]
	v_add_f32_e32 v116, v117, v116
	v_pk_add_f32 v[114:115], v[114:115], v[86:87] op_sel_hi:[1,0] neg_lo:[0,1] neg_hi:[0,1]
	v_add_f32_e32 v116, v120, v116
	v_pk_mul_f32 v[122:123], v[114:115], v[114:115]
	v_add_f32_e32 v116, v121, v116
	v_pk_add_f32 v[112:113], v[112:113], v[86:87] op_sel_hi:[1,0] neg_lo:[0,1] neg_hi:[0,1]
	v_add_f32_e32 v116, v122, v116
	v_pk_mul_f32 v[124:125], v[112:113], v[112:113]
	v_add_f32_e32 v116, v123, v116
	v_pk_add_f32 v[130:131], v[148:149], v[86:87] op_sel_hi:[1,0] neg_lo:[0,1] neg_hi:[0,1]
	v_add_f32_e32 v116, v124, v116
	v_pk_mul_f32 v[132:133], v[130:131], v[130:131]
	v_add_f32_e32 v116, v125, v116
	v_pk_add_f32 v[144:145], v[144:145], v[86:87] op_sel_hi:[1,0] neg_lo:[0,1] neg_hi:[0,1]
	v_add_f32_e32 v116, v132, v116
	v_pk_mul_f32 v[146:147], v[144:145], v[144:145]
	v_add_f32_e32 v116, v133, v116
	v_pk_add_f32 v[142:143], v[142:143], v[86:87] op_sel_hi:[1,0] neg_lo:[0,1] neg_hi:[0,1]
	v_add_f32_e32 v116, v146, v116
	v_pk_mul_f32 v[148:149], v[142:143], v[142:143]
	v_add_f32_e32 v116, v147, v116
	v_pk_add_f32 v[154:155], v[12:13], v[86:87] op_sel_hi:[1,0] neg_lo:[0,1] neg_hi:[0,1]
	v_add_f32_e32 v116, v148, v116
	v_pk_mul_f32 v[156:157], v[154:155], v[154:155]
	v_add_f32_e32 v116, v149, v116
	v_pk_add_f32 v[176:177], v[80:81], v[86:87] op_sel_hi:[1,0] neg_lo:[0,1] neg_hi:[0,1]
	v_add_f32_e32 v116, v156, v116
	v_pk_mul_f32 v[80:81], v[176:177], v[176:177]
	v_add_f32_e32 v116, v157, v116
	v_pk_add_f32 v[96:97], v[96:97], v[86:87] op_sel_hi:[1,0] neg_lo:[0,1] neg_hi:[0,1]
	v_add_f32_e32 v80, v80, v116
	v_pk_mul_f32 v[174:175], v[96:97], v[96:97]
	v_add_f32_e32 v80, v81, v80
	v_pk_add_f32 v[172:173], v[82:83], v[86:87] op_sel_hi:[1,0] neg_lo:[0,1] neg_hi:[0,1]
	v_add_f32_e32 v80, v174, v80
	v_pk_mul_f32 v[82:83], v[172:173], v[172:173]
	v_add_f32_e32 v80, v175, v80
	v_pk_add_f32 v[94:95], v[94:95], v[86:87] op_sel_hi:[1,0] neg_lo:[0,1] neg_hi:[0,1]
	v_add_f32_e32 v80, v82, v80
	v_pk_mul_f32 v[170:171], v[94:95], v[94:95]
	v_add_f32_e32 v80, v83, v80
	v_pk_add_f32 v[150:151], v[150:151], v[86:87] op_sel_hi:[1,0] neg_lo:[0,1] neg_hi:[0,1]
	v_add_f32_e32 v80, v170, v80
	v_pk_mul_f32 v[158:159], v[150:151], v[150:151]
	v_add_f32_e32 v80, v171, v80
	v_pk_add_f32 v[140:141], v[140:141], v[86:87] op_sel_hi:[1,0] neg_lo:[0,1] neg_hi:[0,1]
	v_add_f32_e32 v80, v158, v80
	v_pk_mul_f32 v[160:161], v[140:141], v[140:141]
	v_add_f32_e32 v80, v159, v80
	v_pk_add_f32 v[100:101], v[100:101], v[86:87] op_sel_hi:[1,0] neg_lo:[0,1] neg_hi:[0,1]
	v_add_f32_e32 v80, v160, v80
	v_pk_mul_f32 v[180:181], v[100:101], v[100:101]
	v_add_f32_e32 v80, v161, v80
	v_pk_add_f32 v[98:99], v[98:99], v[86:87] op_sel_hi:[1,0] neg_lo:[0,1] neg_hi:[0,1]
	v_add_f32_e32 v80, v180, v80
	v_pk_mul_f32 v[178:179], v[98:99], v[98:99]
	v_add_f32_e32 v80, v181, v80
	v_pk_add_f32 v[118:119], v[118:119], v[86:87] op_sel_hi:[1,0] neg_lo:[0,1] neg_hi:[0,1]
	v_add_f32_e32 v80, v178, v80
	v_pk_mul_f32 v[184:185], v[118:119], v[118:119]
	v_add_f32_e32 v80, v179, v80
	v_pk_add_f32 v[162:163], v[6:7], v[86:87] op_sel_hi:[1,0] neg_lo:[0,1] neg_hi:[0,1]
	v_add_f32_e32 v80, v184, v80
	v_pk_mul_f32 v[164:165], v[162:163], v[162:163]
	v_add_f32_e32 v80, v185, v80
	v_pk_add_f32 v[182:183], v[72:73], v[86:87] op_sel_hi:[1,0] neg_lo:[0,1] neg_hi:[0,1]
	v_add_f32_e32 v80, v164, v80
	v_pk_mul_f32 v[72:73], v[182:183], v[182:183]
	v_add_f32_e32 v80, v165, v80
	v_pk_add_f32 v[152:153], v[152:153], v[86:87] op_sel_hi:[1,0] neg_lo:[0,1] neg_hi:[0,1]
	v_add_f32_e32 v72, v72, v80
	v_pk_mul_f32 v[166:167], v[152:153], v[152:153]
	v_add_f32_e32 v72, v73, v72
	v_pk_add_f32 v[192:193], v[74:75], v[86:87] op_sel_hi:[1,0] neg_lo:[0,1] neg_hi:[0,1]
	v_add_f32_e32 v72, v166, v72
	v_mov_b32_e32 v89, v87
	v_pk_mul_f32 v[74:75], v[192:193], v[192:193]
	v_add_f32_e32 v72, v167, v72
	v_pk_add_f32 v[88:89], v[88:89], v[86:87] op_sel_hi:[1,0] neg_lo:[0,1] neg_hi:[0,1]
	v_add_f32_e32 v72, v74, v72
	v_pk_mul_f32 v[190:191], v[88:89], v[88:89]
	v_add_f32_e32 v72, v75, v72
	v_pk_add_f32 v[188:189], v[76:77], v[86:87] op_sel_hi:[1,0] neg_lo:[0,1] neg_hi:[0,1]
	v_add_f32_e32 v72, v190, v72
	v_pk_mul_f32 v[76:77], v[188:189], v[188:189]
	v_add_f32_e32 v72, v191, v72
	v_pk_add_f32 v[186:187], v[70:71], v[86:87] op_sel_hi:[1,0] neg_lo:[0,1] neg_hi:[0,1]
	v_add_f32_e32 v72, v76, v72
	v_pk_mul_f32 v[70:71], v[186:187], v[186:187]
	v_add_f32_e32 v72, v77, v72
	v_pk_add_f32 v[14:15], v[104:105], v[86:87] op_sel_hi:[1,0] neg_lo:[0,1] neg_hi:[0,1]
	v_add_f32_e32 v70, v70, v72
	v_pk_mul_f32 v[104:105], v[14:15], v[14:15]
	v_add_f32_e32 v70, v71, v70
	v_pk_add_f32 v[12:13], v[90:91], v[86:87] op_sel_hi:[1,0] neg_lo:[0,1] neg_hi:[0,1]
	v_add_f32_e32 v70, v104, v70
	v_mov_b32_e32 v138, v17
	v_mov_b32_e32 v139, v135
	v_mov_b32_e32 v135, v16
	v_mov_b32_e32 v16, v126
	v_mov_b32_e32 v17, v128
	v_pk_mul_f32 v[90:91], v[12:13], v[12:13]
	v_add_f32_e32 v70, v105, v70
	v_pk_add_f32 v[16:17], v[16:17], v[86:87] op_sel_hi:[1,0] neg_lo:[0,1] neg_hi:[0,1]
	v_add_f32_e32 v70, v90, v70
	v_pk_mul_f32 v[196:197], v[16:17], v[16:17]
	v_add_f32_e32 v70, v91, v70
	v_pk_add_f32 v[134:135], v[134:135], v[86:87] op_sel_hi:[1,0] neg_lo:[0,1] neg_hi:[0,1]
	v_add_f32_e32 v70, v196, v70
	v_pk_mul_f32 v[194:195], v[134:135], v[134:135]
	v_mov_b32_e32 v128, v127
	v_add_f32_e32 v70, v197, v70
	v_pk_add_f32 v[10:11], v[10:11], v[86:87] op_sel_hi:[1,0] neg_lo:[0,1] neg_hi:[0,1]
	v_pk_add_f32 v[8:9], v[138:139], v[86:87] op_sel_hi:[1,0] neg_lo:[0,1] neg_hi:[0,1]
	v_pk_add_f32 v[6:7], v[136:137], v[86:87] op_sel_hi:[1,0] neg_lo:[0,1] neg_hi:[0,1]
	v_pk_add_f32 v[86:87], v[128:129], v[86:87] op_sel_hi:[1,0] neg_lo:[0,1] neg_hi:[0,1]
	v_add_f32_e32 v70, v194, v70
	v_pk_mul_f32 v[126:127], v[86:87], v[86:87]
	v_add_f32_e32 v70, v195, v70
	v_add_f32_e32 v70, v126, v70
	v_pk_mul_f32 v[168:169], v[10:11], v[10:11]
	v_add_f32_e32 v70, v127, v70
	v_add_f32_e32 v70, v168, v70
	v_pk_mul_f32 v[138:139], v[8:9], v[8:9]
	v_add_f32_e32 v70, v169, v70
	v_add_f32_e32 v70, v139, v70
	v_pk_mul_f32 v[136:137], v[6:7], v[6:7]
	v_add_f32_e32 v70, v138, v70
	v_add_f32_e32 v70, v137, v70
	v_add_f32_e32 v80, v136, v70
	ds_bpermute_b32 v81, v111, v80
	global_load_dwordx4 v[74:77], v[78:79], off offset:2048
	global_load_dwordx4 v[70:73], v[78:79], off offset:3072
	s_barrier
	v_readfirstlane_b32 vcc_lo, v110
	s_nop 0
	s_cmp_lt_i32 vcc_lo, 64
	s_cbranch_scc0 .Lsgu_nogain
	ds_write_b128 v210, v[206:209]
.Lsgu_nogain:
	s_waitcnt lgkmcnt(0)
	s_barrier
	v_add_f32_e32 v78, v80, v81
	ds_bpermute_b32 v79, v198, v78
	v_lshl_add_u32 v80, v85, 2, 0
	v_add_u32_e32 v104, 0x11000, v80
	v_mul_lo_u32 v80, v84, s1
	v_add3_u32 v105, 0, v80, v0
	s_waitcnt lgkmcnt(0)
	v_add_f32_e32 v78, v78, v79
	v_fmamk_f32 v78, v78, 0x3b800000, v202
	v_mul_f32_e32 v79, 0x4b800000, v78
	v_cmp_gt_f32_e32 vcc, s47, v78
	v_and_b32_e32 v111, 31, v110
	s_movk_i32 s1, 0x6000
	v_cndmask_b32_e32 v78, v78, v79, vcc
	v_rsq_f32_e32 v90, v78
	ds_read_b128 v[78:81], v104
	ds_read_b128 v[82:85], v104 offset:16
	v_mul_f32_e32 v0, 0x45800000, v90
	v_cndmask_b32_e32 v0, v90, v0, vcc
	v_pk_mul_f32 v[90:91], v[102:103], v[0:1] op_sel_hi:[1,0]
	v_pk_mul_f32 v[88:89], v[88:89], v[0:1] op_sel_hi:[1,0]
	s_waitcnt lgkmcnt(1)
	v_pk_mul_f32 v[78:79], v[78:79], v[90:91]
	v_pk_mul_f32 v[90:91], v[92:93], v[0:1] op_sel_hi:[1,0]
	v_cvt_pk_bf16_f32 v78, v78, v79
	v_pk_mul_f32 v[80:81], v[80:81], v[90:91]
	v_pk_mul_f32 v[90:91], v[130:131], v[0:1] op_sel_hi:[1,0]
	v_cvt_pk_bf16_f32 v79, v80, v81
	v_pk_mul_f32 v[80:81], v[114:115], v[0:1] op_sel_hi:[1,0]
	v_pk_mul_f32 v[14:15], v[14:15], v[0:1] op_sel_hi:[1,0]
	s_waitcnt lgkmcnt(0)
	v_pk_mul_f32 v[80:81], v[82:83], v[80:81]
	v_pk_mul_f32 v[82:83], v[112:113], v[0:1] op_sel_hi:[1,0]
	v_cvt_pk_bf16_f32 v80, v80, v81
	v_pk_mul_f32 v[82:83], v[84:85], v[82:83]
	v_pk_mul_f32 v[12:13], v[12:13], v[0:1] op_sel_hi:[1,0]
	v_cvt_pk_bf16_f32 v81, v82, v83
	ds_write2_b64 v105, v[78:79], v[80:81] offset1:1
	ds_read_b128 v[78:81], v104 offset:32
	ds_read_b128 v[82:85], v104 offset:48
	v_pk_mul_f32 v[10:11], v[10:11], v[0:1] op_sel_hi:[1,0]
	v_pk_mul_f32 v[8:9], v[8:9], v[0:1] op_sel_hi:[1,0]
	v_pk_mul_f32 v[6:7], v[6:7], v[0:1] op_sel_hi:[1,0]
	s_waitcnt lgkmcnt(1)
	v_pk_mul_f32 v[78:79], v[78:79], v[90:91]
	v_pk_mul_f32 v[90:91], v[144:145], v[0:1] op_sel_hi:[1,0]
	v_cvt_pk_bf16_f32 v78, v78, v79
	v_pk_mul_f32 v[80:81], v[80:81], v[90:91]
	v_pk_mul_f32 v[90:91], v[176:177], v[0:1] op_sel_hi:[1,0]
	v_cvt_pk_bf16_f32 v79, v80, v81
	v_pk_mul_f32 v[80:81], v[142:143], v[0:1] op_sel_hi:[1,0]
	s_waitcnt lgkmcnt(0)
	v_pk_mul_f32 v[80:81], v[82:83], v[80:81]
	v_pk_mul_f32 v[82:83], v[154:155], v[0:1] op_sel_hi:[1,0]
	v_cvt_pk_bf16_f32 v80, v80, v81
	v_pk_mul_f32 v[82:83], v[84:85], v[82:83]
	s_nop 0
	v_cvt_pk_bf16_f32 v81, v82, v83
	ds_write2_b64 v105, v[78:79], v[80:81] offset0:2 offset1:3
	ds_read_b128 v[78:81], v104 offset:64
	ds_read_b128 v[82:85], v104 offset:80
	s_waitcnt lgkmcnt(1)
	v_pk_mul_f32 v[78:79], v[78:79], v[90:91]
	v_pk_mul_f32 v[90:91], v[96:97], v[0:1] op_sel_hi:[1,0]
	v_cvt_pk_bf16_f32 v78, v78, v79
	v_pk_mul_f32 v[80:81], v[80:81], v[90:91]
	v_pk_mul_f32 v[90:91], v[150:151], v[0:1] op_sel_hi:[1,0]
	v_cvt_pk_bf16_f32 v79, v80, v81
	v_pk_mul_f32 v[80:81], v[172:173], v[0:1] op_sel_hi:[1,0]
	s_waitcnt lgkmcnt(0)
	v_pk_mul_f32 v[80:81], v[82:83], v[80:81]
	v_pk_mul_f32 v[82:83], v[94:95], v[0:1] op_sel_hi:[1,0]
	v_cvt_pk_bf16_f32 v80, v80, v81
	v_pk_mul_f32 v[82:83], v[84:85], v[82:83]
	s_nop 0
	v_cvt_pk_bf16_f32 v81, v82, v83
	ds_write2_b64 v105, v[78:79], v[80:81] offset0:4 offset1:5
	ds_read_b128 v[78:81], v104 offset:96
	ds_read_b128 v[82:85], v104 offset:112
	s_waitcnt lgkmcnt(1)
	v_pk_mul_f32 v[78:79], v[78:79], v[90:91]
	v_pk_mul_f32 v[90:91], v[140:141], v[0:1] op_sel_hi:[1,0]
	v_cvt_pk_bf16_f32 v78, v78, v79
	v_pk_mul_f32 v[80:81], v[80:81], v[90:91]
	v_pk_mul_f32 v[90:91], v[118:119], v[0:1] op_sel_hi:[1,0]
	v_cvt_pk_bf16_f32 v79, v80, v81
	v_pk_mul_f32 v[80:81], v[100:101], v[0:1] op_sel_hi:[1,0]
	s_waitcnt lgkmcnt(0)
	v_pk_mul_f32 v[80:81], v[82:83], v[80:81]
	v_pk_mul_f32 v[82:83], v[98:99], v[0:1] op_sel_hi:[1,0]
	v_cvt_pk_bf16_f32 v80, v80, v81
	v_pk_mul_f32 v[82:83], v[84:85], v[82:83]
	s_nop 0
	v_cvt_pk_bf16_f32 v81, v82, v83
	ds_write2_b64 v105, v[78:79], v[80:81] offset0:6 offset1:7
	ds_read_b128 v[78:81], v104 offset:128
	ds_read_b128 v[82:85], v104 offset:144
	s_waitcnt lgkmcnt(1)
	v_pk_mul_f32 v[78:79], v[78:79], v[90:91]
	v_pk_mul_f32 v[90:91], v[162:163], v[0:1] op_sel_hi:[1,0]
	v_cvt_pk_bf16_f32 v78, v78, v79
	v_pk_mul_f32 v[80:81], v[80:81], v[90:91]
	v_pk_mul_f32 v[90:91], v[192:193], v[0:1] op_sel_hi:[1,0]
	v_cvt_pk_bf16_f32 v79, v80, v81
	v_pk_mul_f32 v[80:81], v[182:183], v[0:1] op_sel_hi:[1,0]
	s_waitcnt lgkmcnt(0)
	v_pk_mul_f32 v[80:81], v[82:83], v[80:81]
	v_pk_mul_f32 v[82:83], v[152:153], v[0:1] op_sel_hi:[1,0]
	v_cvt_pk_bf16_f32 v80, v80, v81
	v_pk_mul_f32 v[82:83], v[84:85], v[82:83]
	s_nop 0
	v_cvt_pk_bf16_f32 v81, v82, v83
	ds_write2_b64 v105, v[78:79], v[80:81] offset0:8 offset1:9
	ds_read_b128 v[78:81], v104 offset:160
	ds_read_b128 v[82:85], v104 offset:176
	s_waitcnt lgkmcnt(1)
	v_pk_mul_f32 v[78:79], v[78:79], v[90:91]
	v_pk_mul_f32 v[80:81], v[80:81], v[88:89]
	v_cvt_pk_bf16_f32 v78, v78, v79
	v_cvt_pk_bf16_f32 v79, v80, v81
	v_pk_mul_f32 v[80:81], v[188:189], v[0:1] op_sel_hi:[1,0]
	s_waitcnt lgkmcnt(0)
	v_pk_mul_f32 v[80:81], v[82:83], v[80:81]
	v_pk_mul_f32 v[82:83], v[186:187], v[0:1] op_sel_hi:[1,0]
	v_cvt_pk_bf16_f32 v80, v80, v81
	v_pk_mul_f32 v[82:83], v[84:85], v[82:83]
	s_nop 0
	v_cvt_pk_bf16_f32 v81, v82, v83
	ds_write2_b64 v105, v[78:79], v[80:81] offset0:10 offset1:11
	ds_read_b128 v[78:81], v104 offset:192
	ds_read_b128 v[82:85], v104 offset:208
	s_waitcnt lgkmcnt(1)
	v_pk_mul_f32 v[14:15], v[78:79], v[14:15]
	v_pk_mul_f32 v[12:13], v[80:81], v[12:13]
	v_cvt_pk_bf16_f32 v14, v14, v15
	v_cvt_pk_bf16_f32 v15, v12, v13
	v_pk_mul_f32 v[12:13], v[16:17], v[0:1] op_sel_hi:[1,0]
	v_pk_mul_f32 v[16:17], v[134:135], v[0:1] op_sel_hi:[1,0]
	s_waitcnt lgkmcnt(0)
	v_pk_mul_f32 v[12:13], v[82:83], v[12:13]
	v_pk_mul_f32 v[16:17], v[84:85], v[16:17]
	v_cvt_pk_bf16_f32 v12, v12, v13
	v_cvt_pk_bf16_f32 v13, v16, v17
	ds_write2_b64 v105, v[14:15], v[12:13] offset0:12 offset1:13
	ds_read_b128 v[12:15], v104 offset:224
	ds_read_b128 v[78:81], v104 offset:240
	v_pk_mul_f32 v[16:17], v[86:87], v[0:1] op_sel_hi:[1,0]
	v_lshrrev_b32_e32 v0, 2, v110
	v_and_b32_e32 v141, 8, v0
	v_and_b32_e32 v0, 0xffffffc0, v110
	s_waitcnt lgkmcnt(0)
	v_pk_mul_f32 v[8:9], v[78:79], v[8:9] op_sel:[0,1] op_sel_hi:[1,0]
	v_pk_mul_f32 v[6:7], v[80:81], v[6:7] op_sel:[0,1] op_sel_hi:[1,0]
	v_pk_mul_f32 v[12:13], v[12:13], v[16:17]
	v_pk_mul_f32 v[10:11], v[14:15], v[10:11]
	v_cvt_pk_bf16_f32 v8, v8, v9
	v_cvt_pk_bf16_f32 v9, v6, v7
	v_add_u32_e32 v142, 0, v0
	v_lshlrev_b32_e32 v0, 1, v111
	v_mul_u32_u24_e32 v6, 0x208, v141
	v_cvt_pk_bf16_f32 v12, v12, v13
	v_cvt_pk_bf16_f32 v13, v10, v11
	v_add3_u32 v0, v142, v0, v6
	ds_write2_b64 v105, v[12:13], v[8:9] offset0:14 offset1:15
	s_waitcnt lgkmcnt(0)
	s_barrier
	ds_read_u16 v6, v0
	ds_read_u16 v7, v0 offset:520
	ds_read_u16 v8, v0 offset:1040
	ds_read_u16 v9, v0 offset:1560
	ds_read_u16 v10, v0 offset:2080
	ds_read_u16 v11, v0 offset:2600
	ds_read_u16 v12, v0 offset:3120
	ds_read_u16 v13, v0 offset:3640
	s_waitcnt lgkmcnt(6)
	v_lshl_or_b32 v78, v7, 16, v6
	s_waitcnt lgkmcnt(4)
	v_lshl_or_b32 v79, v9, 16, v8
	s_waitcnt lgkmcnt(2)
	v_lshl_or_b32 v80, v11, 16, v10
	ds_read_u16 v6, v0 offset:8320
	ds_read_u16 v7, v0 offset:8840
	ds_read_u16 v8, v0 offset:9360
	ds_read_u16 v9, v0 offset:9880
	ds_read_u16 v10, v0 offset:10400
	ds_read_u16 v11, v0 offset:10920
	ds_read_u16 v85, v0 offset:11440
	ds_read_u16 v86, v0 offset:11960
	s_waitcnt lgkmcnt(8)
	v_lshl_or_b32 v81, v13, 16, v12
	s_waitcnt lgkmcnt(6)
	v_lshl_or_b32 v82, v7, 16, v6
	s_waitcnt lgkmcnt(4)
	v_lshl_or_b32 v83, v9, 16, v8
	s_waitcnt lgkmcnt(2)
	v_lshl_or_b32 v84, v11, 16, v10
	v_mfma_f32_32x32x16_bf16 v[2:17], v[78:81], v[2:5], 0
	s_waitcnt lgkmcnt(0)
	v_lshl_or_b32 v85, v86, 16, v85
	ds_read_u16 v87, v0 offset:16640
	ds_read_u16 v88, v0 offset:17160
	ds_read_u16 v89, v0 offset:17680
	ds_read_u16 v90, v0 offset:18200
	ds_read_u16 v91, v0 offset:18720
	ds_read_u16 v92, v0 offset:19240
	ds_read_u16 v93, v0 offset:19760
	ds_read_u16 v94, v0 offset:20280
	s_waitcnt lgkmcnt(6)
	v_lshl_or_b32 v86, v88, 16, v87
	s_waitcnt lgkmcnt(4)
	v_lshl_or_b32 v87, v90, 16, v89
	s_waitcnt lgkmcnt(2)
	v_lshl_or_b32 v88, v92, 16, v91
	s_waitcnt lgkmcnt(0)
	v_lshl_or_b32 v89, v94, 16, v93
	v_mfma_f32_32x32x16_bf16 v[2:17], v[82:85], v[26:29], v[2:17]
	ds_read_u16 v26, v0 offset:24960
	ds_read_u16 v27, v0 offset:25480
	ds_read_u16 v28, v0 offset:26000
	ds_read_u16 v29, v0 offset:26520
	ds_read_u16 v92, v0 offset:27040
	ds_read_u16 v93, v0 offset:27560
	ds_read_u16 v94, v0 offset:28080
	ds_read_u16 v95, v0 offset:28600
	s_waitcnt lgkmcnt(6)
	v_lshl_or_b32 v90, v27, 16, v26
	s_waitcnt lgkmcnt(4)
	v_lshl_or_b32 v91, v29, 16, v28
	s_waitcnt lgkmcnt(2)
	v_lshl_or_b32 v92, v93, 16, v92
	s_waitcnt lgkmcnt(0)
	v_lshl_or_b32 v93, v95, 16, v94
	v_mfma_f32_32x32x16_bf16 v[2:17], v[86:89], v[22:25], v[2:17]
	ds_read_u16 v22, v0 offset:33280
	ds_read_u16 v23, v0 offset:33800
	ds_read_u16 v24, v0 offset:34320
	ds_read_u16 v25, v0 offset:34840
	ds_read_u16 v26, v0 offset:35360
	ds_read_u16 v27, v0 offset:35880
	ds_read_u16 v28, v0 offset:36400
	ds_read_u16 v29, v0 offset:36920
	s_waitcnt lgkmcnt(6)
	v_lshl_or_b32 v94, v23, 16, v22
	s_waitcnt lgkmcnt(4)
	v_lshl_or_b32 v95, v25, 16, v24
	s_waitcnt lgkmcnt(2)
	v_lshl_or_b32 v96, v27, 16, v26
	s_waitcnt lgkmcnt(0)
	v_lshl_or_b32 v97, v29, 16, v28
	v_mfma_f32_32x32x16_bf16 v[2:17], v[90:93], v[18:21], v[2:17]
	ds_read_u16 v18, v0 offset:41600
	ds_read_u16 v19, v0 offset:42120
	ds_read_u16 v20, v0 offset:42640
	ds_read_u16 v21, v0 offset:43160
	ds_read_u16 v22, v0 offset:43680
	ds_read_u16 v23, v0 offset:44200
	ds_read_u16 v24, v0 offset:44720
	ds_read_u16 v25, v0 offset:45240
	s_waitcnt lgkmcnt(6)
	v_lshl_or_b32 v98, v19, 16, v18
	s_waitcnt lgkmcnt(4)
	v_lshl_or_b32 v99, v21, 16, v20
	s_waitcnt lgkmcnt(2)
	v_lshl_or_b32 v100, v23, 16, v22
	ds_read_u16 v18, v0 offset:49920
	ds_read_u16 v19, v0 offset:50440
	ds_read_u16 v20, v0 offset:50960
	ds_read_u16 v21, v0 offset:51480
	ds_read_u16 v22, v0 offset:52000
	ds_read_u16 v23, v0 offset:52520
	ds_read_u16 v26, v0 offset:53040
	ds_read_u16 v27, v0 offset:53560
	s_waitcnt lgkmcnt(8)
	v_lshl_or_b32 v101, v25, 16, v24
	v_mfma_f32_32x32x16_bf16 v[2:17], v[94:97], v[66:69], v[2:17]
	s_waitcnt lgkmcnt(6)
	v_lshl_or_b32 v66, v19, 16, v18
	s_waitcnt lgkmcnt(4)
	v_lshl_or_b32 v67, v21, 16, v20
	s_waitcnt lgkmcnt(2)
	v_lshl_or_b32 v68, v23, 16, v22
	ds_read_u16 v18, v0 offset:58240
	ds_read_u16 v19, v0 offset:58760
	ds_read_u16 v20, v0 offset:59280
	ds_read_u16 v21, v0 offset:59800
	ds_read_u16 v22, v0 offset:60320
	ds_read_u16 v23, v0 offset:60840
	ds_read_u16 v24, v0 offset:61360
	ds_read_u16 v0, v0 offset:61880
	s_waitcnt lgkmcnt(8)
	v_lshl_or_b32 v69, v27, 16, v26
	s_waitcnt lgkmcnt(6)
	v_lshl_or_b32 v102, v19, 16, v18
	s_waitcnt lgkmcnt(4)
	v_lshl_or_b32 v103, v21, 16, v20
	s_waitcnt lgkmcnt(2)
	v_lshl_or_b32 v104, v23, 16, v22
	s_waitcnt lgkmcnt(0)
	v_lshl_or_b32 v105, v0, 16, v24
	v_mfma_f32_32x32x16_bf16 v[18:33], v[78:81], v[30:33], 0
	v_lshl_or_b32 v0, s0, 7, v111
	v_mfma_f32_32x32x16_bf16 v[18:33], v[82:85], v[50:53], v[18:33]
	global_load_dwordx4 v[50:53], v[108:109], off offset:1024
	v_mfma_f32_32x32x16_bf16 v[18:33], v[86:89], v[46:49], v[18:33]
	v_mfma_f32_32x32x16_bf16 v[18:33], v[90:93], v[42:45], v[18:33]
	global_load_dwordx4 v[42:45], v[108:109], off
	v_mfma_f32_32x32x16_bf16 v[2:17], v[98:101], v[62:65], v[2:17]
	v_mfma_f32_32x32x16_bf16 v[2:17], v[66:69], v[54:57], v[2:17]
	global_load_dwordx4 v[54:57], v[108:109], off offset:2048
	v_mfma_f32_32x32x16_bf16 v[18:33], v[94:97], v[38:41], v[18:33]
	v_mfma_f32_32x32x16_bf16 v[2:17], v[102:105], v[58:61], v[2:17]
	global_load_dwordx4 v[58:61], v[108:109], off offset:3072
	v_add_co_u32_e32 v108, vcc, s1, v106
	s_movk_i32 s1, 0x5000
	s_nop 0
	v_addc_co_u32_e32 v109, vcc, 0, v107, vcc
	global_load_dwordx4 v[62:65], v[108:109], off offset:-4096
	v_mfma_f32_32x32x16_bf16 v[18:33], v[98:101], v[34:37], v[18:33]
	v_add_co_u32_e32 v128, vcc, s1, v106
	s_movk_i32 s1, 0x7000
	s_nop 0
	v_addc_co_u32_e32 v129, vcc, 0, v107, vcc
	v_add_co_u32_e32 v136, vcc, s1, v106
	s_waitcnt vmcnt(6)
	v_mfma_f32_32x32x16_bf16 v[18:33], v[66:69], v[74:77], v[18:33]
	v_addc_co_u32_e32 v137, vcc, 0, v107, vcc
	v_cmp_gt_i32_e32 vcc, s46, v110
	s_waitcnt vmcnt(5)
	v_mfma_f32_32x32x16_bf16 v[18:33], v[102:105], v[70:73], v[18:33]
	global_load_dwordx4 v[70:73], v[128:129], off offset:1024
	global_load_dwordx4 v[74:77], v[128:129], off offset:2048
	global_load_dwordx4 v[112:115], v[108:109], off
	global_load_dwordx4 v[116:119], v[108:109], off offset:1024
	global_load_dwordx4 v[120:123], v[108:109], off offset:2048
	global_load_dwordx4 v[124:127], v[108:109], off offset:3072
	s_waitcnt vmcnt(9)
	v_mfma_f32_32x32x16_bf16 v[34:49], v[78:81], v[42:45], 0
	v_mfma_f32_32x32x16_bf16 v[34:49], v[82:85], v[50:53], v[34:49]
	global_load_dwordx4 v[50:53], v[128:129], off offset:3072
	global_load_dwordx4 v[106:109], v[136:137], off
	s_nop 0
	global_load_dwordx4 v[128:131], v[136:137], off offset:1024
	global_load_dwordx4 v[132:135], v[136:137], off offset:2048
	s_nop 0
	global_load_dwordx4 v[136:139], v[136:137], off offset:3072
	s_barrier
	s_waitcnt vmcnt(13)
	v_mfma_f32_32x32x16_bf16 v[34:49], v[86:89], v[54:57], v[34:49]
	v_lshl_add_u64 v[54:55], v[0:1], 2, s[48:49]
	global_load_dword v0, v[54:55], off
	global_load_dword v140, v[54:55], off offset:128
	s_waitcnt vmcnt(14)
	v_mfma_f32_32x32x16_bf16 v[34:49], v[90:93], v[58:61], v[34:49]
	s_waitcnt vmcnt(13)
	v_mfma_f32_32x32x16_bf16 v[34:49], v[94:97], v[62:65], v[34:49]
	s_waitcnt vmcnt(12)
	v_mfma_f32_32x32x16_bf16 v[34:49], v[98:101], v[70:73], v[34:49]
	global_load_dword v70, v[54:55], off offset:256
	global_load_dword v72, v[54:55], off offset:384
	v_mul_u32_u24_e32 v54, 0x210, v111
	v_add3_u32 v71, v142, v141, v54
	s_waitcnt vmcnt(3)
	v_pk_add_f32 v[2:3], v[0:1], v[2:3] op_sel_hi:[0,1]
	v_mfma_f32_32x32x16_bf16 v[34:49], v[66:69], v[74:77], v[34:49]
	v_add_f32_e64 v4, v0, v4
	v_add_f32_e64 v5, v0, v5
	v_cvt_pk_bf16_f32 v2, v2, v3
	v_cvt_pk_bf16_f32 v3, v4, v5
	v_add_f32_e64 v4, v0, v6
	v_add_f32_e64 v5, v0, v7
	v_pk_add_f32 v[6:7], v[0:1], v[8:9] op_sel_hi:[0,1]
	v_cvt_pk_bf16_f32 v4, v4, v5
	v_cvt_pk_bf16_f32 v5, v6, v7
	v_mfma_f32_32x32x16_bf16 v[34:49], v[102:105], v[50:53], v[34:49]
	ds_write2_b64 v71, v[2:3], v[4:5] offset1:2
	v_add_f32_e64 v2, v0, v10
	v_add_f32_e64 v3, v0, v11
	v_add_f32_e64 v4, v0, v12
	v_add_f32_e64 v5, v0, v13
	v_cvt_pk_bf16_f32 v2, v2, v3
	v_cvt_pk_bf16_f32 v3, v4, v5
	v_pk_add_f32 v[4:5], v[0:1], v[14:15] op_sel_hi:[0,1]
	v_pk_add_f32 v[6:7], v[0:1], v[16:17] op_sel_hi:[0,1]
	v_mfma_f32_32x32x16_bf16 v[50:65], v[78:81], v[112:115], 0
	v_cvt_pk_bf16_f32 v4, v4, v5
	v_cvt_pk_bf16_f32 v5, v6, v7
	ds_write2_b64 v71, v[2:3], v[4:5] offset0:4 offset1:6
	s_waitcnt vmcnt(2)
	v_add_f32_e64 v2, v140, v18
	v_add_f32_e64 v3, v140, v19
	v_pk_add_f32 v[4:5], v[140:141], v[20:21] op_sel_hi:[0,1]
	v_cvt_pk_bf16_f32 v2, v2, v3
	v_cvt_pk_bf16_f32 v3, v4, v5
	v_mfma_f32_32x32x16_bf16 v[50:65], v[82:85], v[116:119], v[50:65]
	v_add_f32_e64 v4, v140, v22
	v_add_f32_e64 v5, v140, v23
	v_add_f32_e64 v6, v140, v24
	v_add_f32_e64 v7, v140, v25
	v_cvt_pk_bf16_f32 v4, v4, v5
	v_cvt_pk_bf16_f32 v5, v6, v7
	v_add_u32_e32 v0, 0x4000, v71
	ds_write2_b64 v0, v[2:3], v[4:5] offset0:64 offset1:66
	v_pk_add_f32 v[2:3], v[140:141], v[26:27] op_sel_hi:[0,1]
	v_mfma_f32_32x32x16_bf16 v[50:65], v[86:89], v[120:123], v[50:65]
	v_add_f32_e64 v4, v140, v28
	v_add_f32_e64 v5, v140, v29
	v_cvt_pk_bf16_f32 v2, v2, v3
	v_cvt_pk_bf16_f32 v3, v4, v5
	v_add_f32_e64 v4, v140, v30
	v_add_f32_e64 v5, v140, v31
	v_pk_add_f32 v[6:7], v[140:141], v[32:33] op_sel_hi:[0,1]
	v_cvt_pk_bf16_f32 v4, v4, v5
	v_cvt_pk_bf16_f32 v5, v6, v7
	v_mfma_f32_32x32x16_bf16 v[50:65], v[90:93], v[124:127], v[50:65]
	ds_write2_b64 v0, v[2:3], v[4:5] offset0:68 offset1:70
	s_waitcnt vmcnt(1)
	v_add_f32_e64 v2, v70, v34
	v_add_f32_e64 v3, v70, v35
	v_add_f32_e64 v4, v70, v36
	v_add_f32_e64 v5, v70, v37
	v_cvt_pk_bf16_f32 v2, v2, v3
	v_cvt_pk_bf16_f32 v3, v4, v5
	v_pk_add_f32 v[4:5], v[70:71], v[38:39] op_sel_hi:[0,1]
	v_pk_add_f32 v[6:7], v[70:71], v[40:41] op_sel_hi:[0,1]
	v_mfma_f32_32x32x16_bf16 v[50:65], v[94:97], v[106:109], v[50:65]
	v_cvt_pk_bf16_f32 v4, v4, v5
	v_cvt_pk_bf16_f32 v5, v6, v7
	v_add_u32_e32 v0, 0x8000, v71
	ds_write2_b64 v0, v[2:3], v[4:5] offset0:128 offset1:130
	v_add_f32_e64 v2, v70, v42
	v_add_f32_e64 v3, v70, v43
	v_pk_add_f32 v[4:5], v[70:71], v[44:45] op_sel_hi:[0,1]
	v_cvt_pk_bf16_f32 v2, v2, v3
	v_mfma_f32_32x32x16_bf16 v[50:65], v[98:101], v[128:131], v[50:65]
	v_cvt_pk_bf16_f32 v3, v4, v5
	v_add_f32_e64 v4, v70, v46
	v_add_f32_e64 v5, v70, v47
	v_add_f32_e64 v6, v70, v48
	v_add_f32_e64 v7, v70, v49
	v_cvt_pk_bf16_f32 v4, v4, v5
	v_cvt_pk_bf16_f32 v5, v6, v7
	ds_write2_b64 v0, v[2:3], v[4:5] offset0:132 offset1:134
	v_add_u32_e32 v0, 0xc000, v71
	v_mfma_f32_32x32x16_bf16 v[50:65], v[66:69], v[132:135], v[50:65]
	v_mfma_f32_32x32x16_bf16 v[50:65], v[102:105], v[136:139], v[50:65]
	s_waitcnt vmcnt(0)
	s_nop 10
	v_pk_add_f32 v[2:3], v[72:73], v[50:51] op_sel_hi:[0,1]
	v_pk_add_f32 v[4:5], v[72:73], v[52:53] op_sel_hi:[0,1]
	v_cvt_pk_bf16_f32 v2, v2, v3
	v_cvt_pk_bf16_f32 v3, v4, v5
	v_pk_add_f32 v[4:5], v[72:73], v[54:55] op_sel_hi:[0,1]
	v_pk_add_f32 v[6:7], v[72:73], v[56:57] op_sel_hi:[0,1]
	v_cvt_pk_bf16_f32 v4, v4, v5
	v_cvt_pk_bf16_f32 v5, v6, v7
	ds_write2_b64 v0, v[2:3], v[4:5] offset0:192 offset1:194
	v_pk_add_f32 v[2:3], v[72:73], v[58:59] op_sel_hi:[0,1]
	v_pk_add_f32 v[4:5], v[72:73], v[60:61] op_sel_hi:[0,1]
	v_cvt_pk_bf16_f32 v2, v2, v3
	v_cvt_pk_bf16_f32 v3, v4, v5
	v_pk_add_f32 v[4:5], v[72:73], v[62:63] op_sel_hi:[0,1]
	v_pk_add_f32 v[6:7], v[72:73], v[64:65] op_sel_hi:[0,1]
	v_cvt_pk_bf16_f32 v4, v4, v5
	v_cvt_pk_bf16_f32 v5, v6, v7
	ds_write2_b64 v0, v[2:3], v[4:5] offset0:196 offset1:198
	s_waitcnt lgkmcnt(0)
	s_barrier
	s_and_saveexec_b64 s[0:1], vcc
	s_cbranch_execz .LBB0_305
	v_max_i32_e32 v2, 0xe00, v110
	v_sub_u32_e32 v2, v2, v110
	v_add_u32_e32 v7, 0x1ff, v2
	v_lshl_or_b32 v0, v111, 3, s28
	v_and_b32_e32 v2, 0x200, v7
	v_lshl_add_u32 v6, v111, 4, 0
	v_cmp_eq_u32_e32 vcc, 0, v2
	v_lshlrev_b32_e32 v0, 1, v0
	s_and_saveexec_b64 s[28:29], vcc
	s_cbranch_execz .LBB0_311
	v_ashrrev_i32_e32 v2, 5, v110
	v_add_u32_e32 v8, s40, v2
	v_mov_b64_e32 v[10:11], s[24:25]
	v_mad_i64_i32 v[10:11], s[44:45], v8, s77, v[10:11]
	v_lshl_add_u64 v[10:11], v[10:11], 0, v[0:1]
	v_add_co_u32_e32 v14, vcc, s34, v10
	v_mad_u64_u32 v[2:3], s[44:45], v2, s69, v[6:7]
	s_nop 0
	v_addc_co_u32_e32 v15, vcc, 0, v11, vcc
	ds_read_b128 v[2:5], v2
	global_load_dwordx4 v[10:13], v[14:15], off offset:-4096
	s_nop 0
	global_load_dwordx4 v[14:17], v[14:15], off
	v_ashrrev_i32_e32 v9, 31, v8
	v_lshlrev_b64 v[8:9], 12, v[8:9]
	v_lshl_add_u64 v[8:9], s[18:19], 0, v[8:9]
	s_waitcnt lgkmcnt(0)
	v_lshlrev_b32_e32 v24, 16, v2
	v_and_b32_e32 v25, 0xffff0000, v2
	v_lshl_add_u64 v[8:9], v[8:9], 0, v[0:1]
	v_add_co_u32_e32 v8, vcc, 0x11848000, v8
	v_add_u32_e32 v110, 0x200, v110
	s_nop 0
	v_addc_co_u32_e32 v9, vcc, 0, v9, vcc
	s_waitcnt vmcnt(1)
	v_lshlrev_b32_e32 v22, 16, v10
	s_waitcnt vmcnt(0)
	v_lshlrev_b32_e32 v18, 16, v14
	v_and_b32_e32 v19, 0xffff0000, v14
	v_mul_f32_e32 v14, 0xbfb8aa3b, v18
	v_mul_f32_e32 v2, 0xbfb8aa3b, v19
	v_exp_f32_e32 v14, v14
	v_exp_f32_e32 v2, v2
	v_and_b32_e32 v23, 0xffff0000, v10
	v_pk_mul_f32 v[22:23], v[24:25], v[22:23]
	v_add_f32_e32 v14, 1.0, v14
	v_add_f32_e32 v2, 1.0, v2
	v_rcp_f32_e32 v20, v14
	v_rcp_f32_e32 v21, v2
	v_lshlrev_b32_e32 v14, 16, v15
	v_and_b32_e32 v15, 0xffff0000, v15
	v_mul_f32_e32 v10, 0xbfb8aa3b, v14
	v_pk_mul_f32 v[18:19], v[20:21], v[18:19]
	v_lshlrev_b32_e32 v20, 16, v3
	v_and_b32_e32 v21, 0xffff0000, v3
	v_mul_f32_e32 v3, 0xbfb8aa3b, v15
	v_exp_f32_e32 v10, v10
	v_exp_f32_e32 v3, v3
	v_pk_mul_f32 v[18:19], v[22:23], v[18:19]
	v_add_f32_e32 v10, 1.0, v10
	v_add_f32_e32 v3, 1.0, v3
	v_cvt_pk_bf16_f32 v2, v18, v19
	v_rcp_f32_e32 v10, v10
	v_lshlrev_b32_e32 v18, 16, v11
	v_and_b32_e32 v19, 0xffff0000, v11
	v_rcp_f32_e32 v11, v3
	v_pk_mul_f32 v[18:19], v[20:21], v[18:19]
	v_lshlrev_b32_e32 v20, 16, v4
	v_and_b32_e32 v21, 0xffff0000, v4
	v_pk_mul_f32 v[10:11], v[10:11], v[14:15]
	s_nop 0
	v_pk_mul_f32 v[10:11], v[18:19], v[10:11]
	v_lshlrev_b32_e32 v18, 16, v12
	v_cvt_pk_bf16_f32 v3, v10, v11
	v_lshlrev_b32_e32 v10, 16, v16
	v_and_b32_e32 v11, 0xffff0000, v16
	v_mul_f32_e32 v14, 0xbfb8aa3b, v10
	v_mul_f32_e32 v4, 0xbfb8aa3b, v11
	v_exp_f32_e32 v14, v14
	v_exp_f32_e32 v4, v4
	v_and_b32_e32 v19, 0xffff0000, v12
	v_pk_mul_f32 v[18:19], v[20:21], v[18:19]
	v_add_f32_e32 v14, 1.0, v14
	v_add_f32_e32 v4, 1.0, v4
	v_rcp_f32_e32 v14, v14
	v_rcp_f32_e32 v15, v4
	v_lshlrev_b32_e32 v16, 16, v5
	v_pk_mul_f32 v[10:11], v[14:15], v[10:11]
	s_nop 0
	v_pk_mul_f32 v[10:11], v[18:19], v[10:11]
	v_lshlrev_b32_e32 v14, 16, v13
	v_cvt_pk_bf16_f32 v4, v10, v11
	v_lshlrev_b32_e32 v10, 16, v17
	v_and_b32_e32 v11, 0xffff0000, v17
	v_mul_f32_e32 v12, 0xbfb8aa3b, v10
	v_and_b32_e32 v17, 0xffff0000, v5
	v_mul_f32_e32 v5, 0xbfb8aa3b, v11
	v_exp_f32_e32 v12, v12
	v_exp_f32_e32 v5, v5
	v_and_b32_e32 v15, 0xffff0000, v13
	v_pk_mul_f32 v[14:15], v[16:17], v[14:15]
	v_add_f32_e32 v12, 1.0, v12
	v_add_f32_e32 v5, 1.0, v5
	v_rcp_f32_e32 v12, v12
	v_rcp_f32_e32 v13, v5
	s_nop 0
	v_pk_mul_f32 v[10:11], v[12:13], v[10:11]
	s_nop 0
	v_pk_mul_f32 v[10:11], v[14:15], v[10:11]
	s_nop 0
	v_cvt_pk_bf16_f32 v5, v10, v11
	global_store_dwordx4 v[8:9], v[2:5], off offset:2048

.LBB0_313:
	v_ashrrev_i32_e32 v2, 5, v110
	v_add_u32_e32 v4, s40, v2
	v_mad_u64_u32 v[2:3], s[44:45], v2, s69, v[6:7]
	v_mov_b64_e32 v[144:145], s[24:25]
	v_mad_i64_i32 v[12:13], s[44:45], v4, s77, v[144:145]
	v_lshl_add_u64 v[12:13], v[12:13], 0, v[0:1]
	v_add_co_u32_e32 v16, vcc, s34, v12
	s_nop 1
	v_addc_co_u32_e32 v17, vcc, 0, v13, vcc
	s_mov_b64 s[44:45], 0x28000
	s_mov_b64 s[28:29], 0x10000
	global_load_dwordx4 v[28:31], v[16:17], off offset:-4096
	global_load_dwordx4 v[60:63], v[16:17], off
	v_lshl_add_u64 v[16:17], v[16:17], 0, s[44:45]
	global_load_dwordx4 v[32:35], v[16:17], off offset:-4096
	global_load_dwordx4 v[64:67], v[16:17], off
	v_lshl_add_u64 v[16:17], v[16:17], 0, s[44:45]
	global_load_dwordx4 v[36:39], v[16:17], off offset:-4096
	global_load_dwordx4 v[68:71], v[16:17], off
	v_lshl_add_u64 v[16:17], v[16:17], 0, s[44:45]
	global_load_dwordx4 v[40:43], v[16:17], off offset:-4096
	global_load_dwordx4 v[72:75], v[16:17], off
	v_lshl_add_u64 v[16:17], v[16:17], 0, s[44:45]
	global_load_dwordx4 v[44:47], v[16:17], off offset:-4096
	global_load_dwordx4 v[76:79], v[16:17], off
	v_lshl_add_u64 v[16:17], v[16:17], 0, s[44:45]
	global_load_dwordx4 v[48:51], v[16:17], off offset:-4096
	global_load_dwordx4 v[80:83], v[16:17], off
	v_lshl_add_u64 v[16:17], v[16:17], 0, s[44:45]
	global_load_dwordx4 v[52:55], v[16:17], off offset:-4096
	global_load_dwordx4 v[84:87], v[16:17], off
	v_lshl_add_u64 v[16:17], v[16:17], 0, s[44:45]
	global_load_dwordx4 v[56:59], v[16:17], off offset:-4096
	global_load_dwordx4 v[88:91], v[16:17], off
	ds_read_b128 v[112:115], v2
	ds_read_b128 v[116:119], v2 offset:8448
	ds_read_b128 v[120:123], v2 offset:16896
	ds_read_b128 v[124:127], v2 offset:25344
	ds_read_b128 v[128:131], v2 offset:33792
	ds_read_b128 v[132:135], v2 offset:42240
	ds_read_b128 v[136:139], v2 offset:50688
	ds_read_b128 v[140:143], v2 offset:59136
	v_ashrrev_i32_e32 v5, 31, v4
	v_lshlrev_b64 v[4:5], 12, v[4:5]
	v_lshl_add_u64 v[4:5], s[18:19], 0, v[4:5]
	v_lshl_add_u64 v[4:5], v[4:5], 0, v[0:1]
	v_add_co_u32_e32 v4, vcc, 0x11848000, v4
	s_nop 1
	v_addc_co_u32_e32 v5, vcc, 0, v5, vcc
	s_waitcnt lgkmcnt(0)
	s_waitcnt vmcnt(14)
	v_lshlrev_b32_e32 v26, 16, v112
	v_and_b32_e32 v27, 0xffff0000, v112
	v_lshlrev_b32_e32 v24, 16, v28
	v_lshlrev_b32_e32 v20, 16, v60
	v_mul_f32_e32 v7, 0xbfb8aa3b, v20
	v_exp_f32_e32 v7, v7
	v_and_b32_e32 v21, 0xffff0000, v60
	v_lshlrev_b32_e32 v60, 16, v61
	v_and_b32_e32 v61, 0xffff0000, v61
	v_add_f32_e32 v7, 1.0, v7
	v_rcp_f32_e32 v22, v7
	v_mul_f32_e32 v7, 0xbfb8aa3b, v21
	v_exp_f32_e32 v7, v7
	v_and_b32_e32 v25, 0xffff0000, v28
	v_pk_mul_f32 v[24:25], v[26:27], v[24:25]
	v_add_f32_e32 v7, 1.0, v7
	v_rcp_f32_e32 v23, v7
	v_mul_f32_e32 v7, 0xbfb8aa3b, v60
	v_exp_f32_e32 v7, v7
	v_pk_mul_f32 v[20:21], v[22:23], v[20:21]
	s_nop 0
	v_pk_mul_f32 v[20:21], v[24:25], v[20:21]
	v_add_f32_e32 v7, 1.0, v7
	v_rcp_f32_e32 v28, v7
	v_mul_f32_e32 v7, 0xbfb8aa3b, v61
	v_exp_f32_e32 v7, v7
	v_cvt_pk_bf16_f32 v112, v20, v21
	v_lshlrev_b32_e32 v20, 16, v29
	v_and_b32_e32 v21, 0xffff0000, v29
	v_add_f32_e32 v7, 1.0, v7
	v_rcp_f32_e32 v29, v7
	v_lshlrev_b32_e32 v22, 16, v113
	v_and_b32_e32 v23, 0xffff0000, v113
	v_pk_mul_f32 v[20:21], v[22:23], v[20:21]
	v_pk_mul_f32 v[28:29], v[28:29], v[60:61]
	v_lshlrev_b32_e32 v22, 16, v114
	v_pk_mul_f32 v[28:29], v[20:21], v[28:29]
	v_lshlrev_b32_e32 v20, 16, v30
	v_cvt_pk_bf16_f32 v113, v28, v29
	v_lshlrev_b32_e32 v28, 16, v62
	v_mul_f32_e32 v7, 0xbfb8aa3b, v28
	v_exp_f32_e32 v7, v7
	v_and_b32_e32 v29, 0xffff0000, v62
	v_and_b32_e32 v21, 0xffff0000, v30
	v_and_b32_e32 v23, 0xffff0000, v114
	v_add_f32_e32 v7, 1.0, v7
	v_rcp_f32_e32 v60, v7
	v_mul_f32_e32 v7, 0xbfb8aa3b, v29
	v_exp_f32_e32 v7, v7
	v_pk_mul_f32 v[20:21], v[22:23], v[20:21]
	v_lshlrev_b32_e32 v62, 16, v115
	v_add_f32_e32 v7, 1.0, v7
	v_rcp_f32_e32 v61, v7
	s_nop 0
	v_pk_mul_f32 v[28:29], v[60:61], v[28:29]
	s_nop 0
	v_pk_mul_f32 v[28:29], v[20:21], v[28:29]
	v_lshlrev_b32_e32 v60, 16, v31
	v_cvt_pk_bf16_f32 v114, v28, v29
	v_lshlrev_b32_e32 v28, 16, v63
	v_mul_f32_e32 v7, 0xbfb8aa3b, v28
	v_exp_f32_e32 v7, v7
	v_and_b32_e32 v29, 0xffff0000, v63
	v_and_b32_e32 v61, 0xffff0000, v31
	v_and_b32_e32 v63, 0xffff0000, v115
	v_add_f32_e32 v7, 1.0, v7
	v_rcp_f32_e32 v30, v7
	v_mul_f32_e32 v7, 0xbfb8aa3b, v29
	v_exp_f32_e32 v7, v7
	v_pk_mul_f32 v[60:61], v[62:63], v[60:61]
	v_add_f32_e32 v7, 1.0, v7
	v_rcp_f32_e32 v31, v7
	s_nop 0
	v_pk_mul_f32 v[28:29], v[30:31], v[28:29]
	s_nop 0
	v_pk_mul_f32 v[28:29], v[60:61], v[28:29]
	s_nop 0
	v_cvt_pk_bf16_f32 v115, v28, v29
	global_store_dwordx4 v[4:5], v[112:115], off offset:2048
	v_lshl_add_u64 v[4:5], v[4:5], 0, s[28:29]
	s_waitcnt vmcnt(13)
	v_lshlrev_b32_e32 v26, 16, v116
	v_and_b32_e32 v27, 0xffff0000, v116
	v_lshlrev_b32_e32 v24, 16, v32
	v_lshlrev_b32_e32 v20, 16, v64
	v_mul_f32_e32 v7, 0xbfb8aa3b, v20
	v_exp_f32_e32 v7, v7
	v_and_b32_e32 v21, 0xffff0000, v64
	v_lshlrev_b32_e32 v64, 16, v65
	v_and_b32_e32 v65, 0xffff0000, v65
	v_add_f32_e32 v7, 1.0, v7
	v_rcp_f32_e32 v22, v7
	v_mul_f32_e32 v7, 0xbfb8aa3b, v21
	v_exp_f32_e32 v7, v7
	v_and_b32_e32 v25, 0xffff0000, v32
	v_pk_mul_f32 v[24:25], v[26:27], v[24:25]
	v_add_f32_e32 v7, 1.0, v7
	v_rcp_f32_e32 v23, v7
	v_mul_f32_e32 v7, 0xbfb8aa3b, v64
	v_exp_f32_e32 v7, v7
	v_pk_mul_f32 v[20:21], v[22:23], v[20:21]
	s_nop 0
	v_pk_mul_f32 v[20:21], v[24:25], v[20:21]
	v_add_f32_e32 v7, 1.0, v7
	v_rcp_f32_e32 v32, v7
	v_mul_f32_e32 v7, 0xbfb8aa3b, v65
	v_exp_f32_e32 v7, v7
	v_cvt_pk_bf16_f32 v116, v20, v21
	v_lshlrev_b32_e32 v20, 16, v33
	v_and_b32_e32 v21, 0xffff0000, v33
	v_add_f32_e32 v7, 1.0, v7
	v_rcp_f32_e32 v33, v7
	v_lshlrev_b32_e32 v22, 16, v117
	v_and_b32_e32 v23, 0xffff0000, v117
	v_pk_mul_f32 v[20:21], v[22:23], v[20:21]
	v_pk_mul_f32 v[32:33], v[32:33], v[64:65]
	v_lshlrev_b32_e32 v22, 16, v118
	v_pk_mul_f32 v[32:33], v[20:21], v[32:33]
	v_lshlrev_b32_e32 v20, 16, v34
	v_cvt_pk_bf16_f32 v117, v32, v33
	v_lshlrev_b32_e32 v32, 16, v66
	v_mul_f32_e32 v7, 0xbfb8aa3b, v32
	v_exp_f32_e32 v7, v7
	v_and_b32_e32 v33, 0xffff0000, v66
	v_and_b32_e32 v21, 0xffff0000, v34
	v_and_b32_e32 v23, 0xffff0000, v118
	v_add_f32_e32 v7, 1.0, v7
	v_rcp_f32_e32 v64, v7
	v_mul_f32_e32 v7, 0xbfb8aa3b, v33
	v_exp_f32_e32 v7, v7
	v_pk_mul_f32 v[20:21], v[22:23], v[20:21]
	v_lshlrev_b32_e32 v66, 16, v119
	v_add_f32_e32 v7, 1.0, v7
	v_rcp_f32_e32 v65, v7
	s_nop 0
	v_pk_mul_f32 v[32:33], v[64:65], v[32:33]
	s_nop 0
	v_pk_mul_f32 v[32:33], v[20:21], v[32:33]
	v_lshlrev_b32_e32 v64, 16, v35
	v_cvt_pk_bf16_f32 v118, v32, v33
	v_lshlrev_b32_e32 v32, 16, v67
	v_mul_f32_e32 v7, 0xbfb8aa3b, v32
	v_exp_f32_e32 v7, v7
	v_and_b32_e32 v33, 0xffff0000, v67
	v_and_b32_e32 v65, 0xffff0000, v35
	v_and_b32_e32 v67, 0xffff0000, v119
	v_add_f32_e32 v7, 1.0, v7
	v_rcp_f32_e32 v34, v7
	v_mul_f32_e32 v7, 0xbfb8aa3b, v33
	v_exp_f32_e32 v7, v7
	v_pk_mul_f32 v[64:65], v[66:67], v[64:65]
	v_add_f32_e32 v7, 1.0, v7
	v_rcp_f32_e32 v35, v7
	s_nop 0
	v_pk_mul_f32 v[32:33], v[34:35], v[32:33]
	s_nop 0
	v_pk_mul_f32 v[32:33], v[64:65], v[32:33]
	s_nop 0
	v_cvt_pk_bf16_f32 v119, v32, v33
	global_store_dwordx4 v[4:5], v[116:119], off offset:2048
	v_lshl_add_u64 v[4:5], v[4:5], 0, s[28:29]
	s_waitcnt vmcnt(12)
	v_lshlrev_b32_e32 v26, 16, v120
	v_and_b32_e32 v27, 0xffff0000, v120
	v_lshlrev_b32_e32 v24, 16, v36
	v_lshlrev_b32_e32 v20, 16, v68
	v_mul_f32_e32 v7, 0xbfb8aa3b, v20
	v_exp_f32_e32 v7, v7
	v_and_b32_e32 v21, 0xffff0000, v68
	v_lshlrev_b32_e32 v68, 16, v69
	v_and_b32_e32 v69, 0xffff0000, v69
	v_add_f32_e32 v7, 1.0, v7
	v_rcp_f32_e32 v22, v7
	v_mul_f32_e32 v7, 0xbfb8aa3b, v21
	v_exp_f32_e32 v7, v7
	v_and_b32_e32 v25, 0xffff0000, v36
	v_pk_mul_f32 v[24:25], v[26:27], v[24:25]
	v_add_f32_e32 v7, 1.0, v7
	v_rcp_f32_e32 v23, v7
	v_mul_f32_e32 v7, 0xbfb8aa3b, v68
	v_exp_f32_e32 v7, v7
	v_pk_mul_f32 v[20:21], v[22:23], v[20:21]
	s_nop 0
	v_pk_mul_f32 v[20:21], v[24:25], v[20:21]
	v_add_f32_e32 v7, 1.0, v7
	v_rcp_f32_e32 v36, v7
	v_mul_f32_e32 v7, 0xbfb8aa3b, v69
	v_exp_f32_e32 v7, v7
	v_cvt_pk_bf16_f32 v120, v20, v21
	v_lshlrev_b32_e32 v20, 16, v37
	v_and_b32_e32 v21, 0xffff0000, v37
	v_add_f32_e32 v7, 1.0, v7
	v_rcp_f32_e32 v37, v7
	v_lshlrev_b32_e32 v22, 16, v121
	v_and_b32_e32 v23, 0xffff0000, v121
	v_pk_mul_f32 v[20:21], v[22:23], v[20:21]
	v_pk_mul_f32 v[36:37], v[36:37], v[68:69]
	v_lshlrev_b32_e32 v22, 16, v122
	v_pk_mul_f32 v[36:37], v[20:21], v[36:37]
	v_lshlrev_b32_e32 v20, 16, v38
	v_cvt_pk_bf16_f32 v121, v36, v37
	v_lshlrev_b32_e32 v36, 16, v70
	v_mul_f32_e32 v7, 0xbfb8aa3b, v36
	v_exp_f32_e32 v7, v7
	v_and_b32_e32 v37, 0xffff0000, v70
	v_and_b32_e32 v21, 0xffff0000, v38
	v_and_b32_e32 v23, 0xffff0000, v122
	v_add_f32_e32 v7, 1.0, v7
	v_rcp_f32_e32 v68, v7
	v_mul_f32_e32 v7, 0xbfb8aa3b, v37
	v_exp_f32_e32 v7, v7
	v_pk_mul_f32 v[20:21], v[22:23], v[20:21]
	v_lshlrev_b32_e32 v70, 16, v123
	v_add_f32_e32 v7, 1.0, v7
	v_rcp_f32_e32 v69, v7
	s_nop 0
	v_pk_mul_f32 v[36:37], v[68:69], v[36:37]
	s_nop 0
	v_pk_mul_f32 v[36:37], v[20:21], v[36:37]
	v_lshlrev_b32_e32 v68, 16, v39
	v_cvt_pk_bf16_f32 v122, v36, v37
	v_lshlrev_b32_e32 v36, 16, v71
	v_mul_f32_e32 v7, 0xbfb8aa3b, v36
	v_exp_f32_e32 v7, v7
	v_and_b32_e32 v37, 0xffff0000, v71
	v_and_b32_e32 v69, 0xffff0000, v39
	v_and_b32_e32 v71, 0xffff0000, v123
	v_add_f32_e32 v7, 1.0, v7
	v_rcp_f32_e32 v38, v7
	v_mul_f32_e32 v7, 0xbfb8aa3b, v37
	v_exp_f32_e32 v7, v7
	v_pk_mul_f32 v[68:69], v[70:71], v[68:69]
	v_add_f32_e32 v7, 1.0, v7
	v_rcp_f32_e32 v39, v7
	s_nop 0
	v_pk_mul_f32 v[36:37], v[38:39], v[36:37]
	s_nop 0
	v_pk_mul_f32 v[36:37], v[68:69], v[36:37]
	s_nop 0
	v_cvt_pk_bf16_f32 v123, v36, v37
	global_store_dwordx4 v[4:5], v[120:123], off offset:2048
	v_lshl_add_u64 v[4:5], v[4:5], 0, s[28:29]
	s_waitcnt vmcnt(11)
	v_lshlrev_b32_e32 v26, 16, v124
	v_and_b32_e32 v27, 0xffff0000, v124
	v_lshlrev_b32_e32 v24, 16, v40
	v_lshlrev_b32_e32 v20, 16, v72
	v_mul_f32_e32 v7, 0xbfb8aa3b, v20
	v_exp_f32_e32 v7, v7
	v_and_b32_e32 v21, 0xffff0000, v72
	v_lshlrev_b32_e32 v72, 16, v73
	v_and_b32_e32 v73, 0xffff0000, v73
	v_add_f32_e32 v7, 1.0, v7
	v_rcp_f32_e32 v22, v7
	v_mul_f32_e32 v7, 0xbfb8aa3b, v21
	v_exp_f32_e32 v7, v7
	v_and_b32_e32 v25, 0xffff0000, v40
	v_pk_mul_f32 v[24:25], v[26:27], v[24:25]
	v_add_f32_e32 v7, 1.0, v7
	v_rcp_f32_e32 v23, v7
	v_mul_f32_e32 v7, 0xbfb8aa3b, v72
	v_exp_f32_e32 v7, v7
	v_pk_mul_f32 v[20:21], v[22:23], v[20:21]
	s_nop 0
	v_pk_mul_f32 v[20:21], v[24:25], v[20:21]
	v_add_f32_e32 v7, 1.0, v7
	v_rcp_f32_e32 v40, v7
	v_mul_f32_e32 v7, 0xbfb8aa3b, v73
	v_exp_f32_e32 v7, v7
	v_cvt_pk_bf16_f32 v124, v20, v21
	v_lshlrev_b32_e32 v20, 16, v41
	v_and_b32_e32 v21, 0xffff0000, v41
	v_add_f32_e32 v7, 1.0, v7
	v_rcp_f32_e32 v41, v7
	v_lshlrev_b32_e32 v22, 16, v125
	v_and_b32_e32 v23, 0xffff0000, v125
	v_pk_mul_f32 v[20:21], v[22:23], v[20:21]
	v_pk_mul_f32 v[40:41], v[40:41], v[72:73]
	v_lshlrev_b32_e32 v22, 16, v126
	v_pk_mul_f32 v[40:41], v[20:21], v[40:41]
	v_lshlrev_b32_e32 v20, 16, v42
	v_cvt_pk_bf16_f32 v125, v40, v41
	v_lshlrev_b32_e32 v40, 16, v74
	v_mul_f32_e32 v7, 0xbfb8aa3b, v40
	v_exp_f32_e32 v7, v7
	v_and_b32_e32 v41, 0xffff0000, v74
	v_and_b32_e32 v21, 0xffff0000, v42
	v_and_b32_e32 v23, 0xffff0000, v126
	v_add_f32_e32 v7, 1.0, v7
	v_rcp_f32_e32 v72, v7
	v_mul_f32_e32 v7, 0xbfb8aa3b, v41
	v_exp_f32_e32 v7, v7
	v_pk_mul_f32 v[20:21], v[22:23], v[20:21]
	v_lshlrev_b32_e32 v74, 16, v127
	v_add_f32_e32 v7, 1.0, v7
	v_rcp_f32_e32 v73, v7
	s_nop 0
	v_pk_mul_f32 v[40:41], v[72:73], v[40:41]
	s_nop 0
	v_pk_mul_f32 v[40:41], v[20:21], v[40:41]
	v_lshlrev_b32_e32 v72, 16, v43
	v_cvt_pk_bf16_f32 v126, v40, v41
	v_lshlrev_b32_e32 v40, 16, v75
	v_mul_f32_e32 v7, 0xbfb8aa3b, v40
	v_exp_f32_e32 v7, v7
	v_and_b32_e32 v41, 0xffff0000, v75
	v_and_b32_e32 v73, 0xffff0000, v43
	v_and_b32_e32 v75, 0xffff0000, v127
	v_add_f32_e32 v7, 1.0, v7
	v_rcp_f32_e32 v42, v7
	v_mul_f32_e32 v7, 0xbfb8aa3b, v41
	v_exp_f32_e32 v7, v7
	v_pk_mul_f32 v[72:73], v[74:75], v[72:73]
	v_add_f32_e32 v7, 1.0, v7
	v_rcp_f32_e32 v43, v7
	s_nop 0
	v_pk_mul_f32 v[40:41], v[42:43], v[40:41]
	s_nop 0
	v_pk_mul_f32 v[40:41], v[72:73], v[40:41]
	s_nop 0
	v_cvt_pk_bf16_f32 v127, v40, v41
	global_store_dwordx4 v[4:5], v[124:127], off offset:2048
	v_lshl_add_u64 v[4:5], v[4:5], 0, s[28:29]
	s_waitcnt vmcnt(10)
	v_lshlrev_b32_e32 v26, 16, v128
	v_and_b32_e32 v27, 0xffff0000, v128
	v_lshlrev_b32_e32 v24, 16, v44
	v_lshlrev_b32_e32 v20, 16, v76
	v_mul_f32_e32 v7, 0xbfb8aa3b, v20
	v_exp_f32_e32 v7, v7
	v_and_b32_e32 v21, 0xffff0000, v76
	v_lshlrev_b32_e32 v76, 16, v77
	v_and_b32_e32 v77, 0xffff0000, v77
	v_add_f32_e32 v7, 1.0, v7
	v_rcp_f32_e32 v22, v7
	v_mul_f32_e32 v7, 0xbfb8aa3b, v21
	v_exp_f32_e32 v7, v7
	v_and_b32_e32 v25, 0xffff0000, v44
	v_pk_mul_f32 v[24:25], v[26:27], v[24:25]
	v_add_f32_e32 v7, 1.0, v7
	v_rcp_f32_e32 v23, v7
	v_mul_f32_e32 v7, 0xbfb8aa3b, v76
	v_exp_f32_e32 v7, v7
	v_pk_mul_f32 v[20:21], v[22:23], v[20:21]
	s_nop 0
	v_pk_mul_f32 v[20:21], v[24:25], v[20:21]
	v_add_f32_e32 v7, 1.0, v7
	v_rcp_f32_e32 v44, v7
	v_mul_f32_e32 v7, 0xbfb8aa3b, v77
	v_exp_f32_e32 v7, v7
	v_cvt_pk_bf16_f32 v128, v20, v21
	v_lshlrev_b32_e32 v20, 16, v45
	v_and_b32_e32 v21, 0xffff0000, v45
	v_add_f32_e32 v7, 1.0, v7
	v_rcp_f32_e32 v45, v7
	v_lshlrev_b32_e32 v22, 16, v129
	v_and_b32_e32 v23, 0xffff0000, v129
	v_pk_mul_f32 v[20:21], v[22:23], v[20:21]
	v_pk_mul_f32 v[44:45], v[44:45], v[76:77]
	v_lshlrev_b32_e32 v22, 16, v130
	v_pk_mul_f32 v[44:45], v[20:21], v[44:45]
	v_lshlrev_b32_e32 v20, 16, v46
	v_cvt_pk_bf16_f32 v129, v44, v45
	v_lshlrev_b32_e32 v44, 16, v78
	v_mul_f32_e32 v7, 0xbfb8aa3b, v44
	v_exp_f32_e32 v7, v7
	v_and_b32_e32 v45, 0xffff0000, v78
	v_and_b32_e32 v21, 0xffff0000, v46
	v_and_b32_e32 v23, 0xffff0000, v130
	v_add_f32_e32 v7, 1.0, v7
	v_rcp_f32_e32 v76, v7
	v_mul_f32_e32 v7, 0xbfb8aa3b, v45
	v_exp_f32_e32 v7, v7
	v_pk_mul_f32 v[20:21], v[22:23], v[20:21]
	v_lshlrev_b32_e32 v78, 16, v131
	v_add_f32_e32 v7, 1.0, v7
	v_rcp_f32_e32 v77, v7
	s_nop 0
	v_pk_mul_f32 v[44:45], v[76:77], v[44:45]
	s_nop 0
	v_pk_mul_f32 v[44:45], v[20:21], v[44:45]
	v_lshlrev_b32_e32 v76, 16, v47
	v_cvt_pk_bf16_f32 v130, v44, v45
	v_lshlrev_b32_e32 v44, 16, v79
	v_mul_f32_e32 v7, 0xbfb8aa3b, v44
	v_exp_f32_e32 v7, v7
	v_and_b32_e32 v45, 0xffff0000, v79
	v_and_b32_e32 v77, 0xffff0000, v47
	v_and_b32_e32 v79, 0xffff0000, v131
	v_add_f32_e32 v7, 1.0, v7
	v_rcp_f32_e32 v46, v7
	v_mul_f32_e32 v7, 0xbfb8aa3b, v45
	v_exp_f32_e32 v7, v7
	v_pk_mul_f32 v[76:77], v[78:79], v[76:77]
	v_add_f32_e32 v7, 1.0, v7
	v_rcp_f32_e32 v47, v7
	s_nop 0
	v_pk_mul_f32 v[44:45], v[46:47], v[44:45]
	s_nop 0
	v_pk_mul_f32 v[44:45], v[76:77], v[44:45]
	s_nop 0
	v_cvt_pk_bf16_f32 v131, v44, v45
	global_store_dwordx4 v[4:5], v[128:131], off offset:2048
	v_lshl_add_u64 v[4:5], v[4:5], 0, s[28:29]
	s_waitcnt vmcnt(9)
	v_lshlrev_b32_e32 v26, 16, v132
	v_and_b32_e32 v27, 0xffff0000, v132
	v_lshlrev_b32_e32 v24, 16, v48
	v_lshlrev_b32_e32 v20, 16, v80
	v_mul_f32_e32 v7, 0xbfb8aa3b, v20
	v_exp_f32_e32 v7, v7
	v_and_b32_e32 v21, 0xffff0000, v80
	v_lshlrev_b32_e32 v80, 16, v81
	v_and_b32_e32 v81, 0xffff0000, v81
	v_add_f32_e32 v7, 1.0, v7
	v_rcp_f32_e32 v22, v7
	v_mul_f32_e32 v7, 0xbfb8aa3b, v21
	v_exp_f32_e32 v7, v7
	v_and_b32_e32 v25, 0xffff0000, v48
	v_pk_mul_f32 v[24:25], v[26:27], v[24:25]
	v_add_f32_e32 v7, 1.0, v7
	v_rcp_f32_e32 v23, v7
	v_mul_f32_e32 v7, 0xbfb8aa3b, v80
	v_exp_f32_e32 v7, v7
	v_pk_mul_f32 v[20:21], v[22:23], v[20:21]
	s_nop 0
	v_pk_mul_f32 v[20:21], v[24:25], v[20:21]
	v_add_f32_e32 v7, 1.0, v7
	v_rcp_f32_e32 v48, v7
	v_mul_f32_e32 v7, 0xbfb8aa3b, v81
	v_exp_f32_e32 v7, v7
	v_cvt_pk_bf16_f32 v132, v20, v21
	v_lshlrev_b32_e32 v20, 16, v49
	v_and_b32_e32 v21, 0xffff0000, v49
	v_add_f32_e32 v7, 1.0, v7
	v_rcp_f32_e32 v49, v7
	v_lshlrev_b32_e32 v22, 16, v133
	v_and_b32_e32 v23, 0xffff0000, v133
	v_pk_mul_f32 v[20:21], v[22:23], v[20:21]
	v_pk_mul_f32 v[48:49], v[48:49], v[80:81]
	v_lshlrev_b32_e32 v22, 16, v134
	v_pk_mul_f32 v[48:49], v[20:21], v[48:49]
	v_lshlrev_b32_e32 v20, 16, v50
	v_cvt_pk_bf16_f32 v133, v48, v49
	v_lshlrev_b32_e32 v48, 16, v82
	v_mul_f32_e32 v7, 0xbfb8aa3b, v48
	v_exp_f32_e32 v7, v7
	v_and_b32_e32 v49, 0xffff0000, v82
	v_and_b32_e32 v21, 0xffff0000, v50
	v_and_b32_e32 v23, 0xffff0000, v134
	v_add_f32_e32 v7, 1.0, v7
	v_rcp_f32_e32 v80, v7
	v_mul_f32_e32 v7, 0xbfb8aa3b, v49
	v_exp_f32_e32 v7, v7
	v_pk_mul_f32 v[20:21], v[22:23], v[20:21]
	v_lshlrev_b32_e32 v82, 16, v135
	v_add_f32_e32 v7, 1.0, v7
	v_rcp_f32_e32 v81, v7
	s_nop 0
	v_pk_mul_f32 v[48:49], v[80:81], v[48:49]
	s_nop 0
	v_pk_mul_f32 v[48:49], v[20:21], v[48:49]
	v_lshlrev_b32_e32 v80, 16, v51
	v_cvt_pk_bf16_f32 v134, v48, v49
	v_lshlrev_b32_e32 v48, 16, v83
	v_mul_f32_e32 v7, 0xbfb8aa3b, v48
	v_exp_f32_e32 v7, v7
	v_and_b32_e32 v49, 0xffff0000, v83
	v_and_b32_e32 v81, 0xffff0000, v51
	v_and_b32_e32 v83, 0xffff0000, v135
	v_add_f32_e32 v7, 1.0, v7
	v_rcp_f32_e32 v50, v7
	v_mul_f32_e32 v7, 0xbfb8aa3b, v49
	v_exp_f32_e32 v7, v7
	v_pk_mul_f32 v[80:81], v[82:83], v[80:81]
	v_add_f32_e32 v7, 1.0, v7
	v_rcp_f32_e32 v51, v7
	s_nop 0
	v_pk_mul_f32 v[48:49], v[50:51], v[48:49]
	s_nop 0
	v_pk_mul_f32 v[48:49], v[80:81], v[48:49]
	s_nop 0
	v_cvt_pk_bf16_f32 v135, v48, v49
	global_store_dwordx4 v[4:5], v[132:135], off offset:2048
	v_lshl_add_u64 v[4:5], v[4:5], 0, s[28:29]
	s_waitcnt vmcnt(8)
	v_lshlrev_b32_e32 v26, 16, v136
	v_and_b32_e32 v27, 0xffff0000, v136
	v_lshlrev_b32_e32 v24, 16, v52
	v_lshlrev_b32_e32 v20, 16, v84
	v_mul_f32_e32 v7, 0xbfb8aa3b, v20
	v_exp_f32_e32 v7, v7
	v_and_b32_e32 v21, 0xffff0000, v84
	v_lshlrev_b32_e32 v84, 16, v85
	v_and_b32_e32 v85, 0xffff0000, v85
	v_add_f32_e32 v7, 1.0, v7
	v_rcp_f32_e32 v22, v7
	v_mul_f32_e32 v7, 0xbfb8aa3b, v21
	v_exp_f32_e32 v7, v7
	v_and_b32_e32 v25, 0xffff0000, v52
	v_pk_mul_f32 v[24:25], v[26:27], v[24:25]
	v_add_f32_e32 v7, 1.0, v7
	v_rcp_f32_e32 v23, v7
	v_mul_f32_e32 v7, 0xbfb8aa3b, v84
	v_exp_f32_e32 v7, v7
	v_pk_mul_f32 v[20:21], v[22:23], v[20:21]
	s_nop 0
	v_pk_mul_f32 v[20:21], v[24:25], v[20:21]
	v_add_f32_e32 v7, 1.0, v7
	v_rcp_f32_e32 v52, v7
	v_mul_f32_e32 v7, 0xbfb8aa3b, v85
	v_exp_f32_e32 v7, v7
	v_cvt_pk_bf16_f32 v136, v20, v21
	v_lshlrev_b32_e32 v20, 16, v53
	v_and_b32_e32 v21, 0xffff0000, v53
	v_add_f32_e32 v7, 1.0, v7
	v_rcp_f32_e32 v53, v7
	v_lshlrev_b32_e32 v22, 16, v137
	v_and_b32_e32 v23, 0xffff0000, v137
	v_pk_mul_f32 v[20:21], v[22:23], v[20:21]
	v_pk_mul_f32 v[52:53], v[52:53], v[84:85]
	v_lshlrev_b32_e32 v22, 16, v138
	v_pk_mul_f32 v[52:53], v[20:21], v[52:53]
	v_lshlrev_b32_e32 v20, 16, v54
	v_cvt_pk_bf16_f32 v137, v52, v53
	v_lshlrev_b32_e32 v52, 16, v86
	v_mul_f32_e32 v7, 0xbfb8aa3b, v52
	v_exp_f32_e32 v7, v7
	v_and_b32_e32 v53, 0xffff0000, v86
	v_and_b32_e32 v21, 0xffff0000, v54
	v_and_b32_e32 v23, 0xffff0000, v138
	v_add_f32_e32 v7, 1.0, v7
	v_rcp_f32_e32 v84, v7
	v_mul_f32_e32 v7, 0xbfb8aa3b, v53
	v_exp_f32_e32 v7, v7
	v_pk_mul_f32 v[20:21], v[22:23], v[20:21]
	v_lshlrev_b32_e32 v86, 16, v139
	v_add_f32_e32 v7, 1.0, v7
	v_rcp_f32_e32 v85, v7
	s_nop 0
	v_pk_mul_f32 v[52:53], v[84:85], v[52:53]
	s_nop 0
	v_pk_mul_f32 v[52:53], v[20:21], v[52:53]
	v_lshlrev_b32_e32 v84, 16, v55
	v_cvt_pk_bf16_f32 v138, v52, v53
	v_lshlrev_b32_e32 v52, 16, v87
	v_mul_f32_e32 v7, 0xbfb8aa3b, v52
	v_exp_f32_e32 v7, v7
	v_and_b32_e32 v53, 0xffff0000, v87
	v_and_b32_e32 v85, 0xffff0000, v55
	v_and_b32_e32 v87, 0xffff0000, v139
	v_add_f32_e32 v7, 1.0, v7
	v_rcp_f32_e32 v54, v7
	v_mul_f32_e32 v7, 0xbfb8aa3b, v53
	v_exp_f32_e32 v7, v7
	v_pk_mul_f32 v[84:85], v[86:87], v[84:85]
	v_add_f32_e32 v7, 1.0, v7
	v_rcp_f32_e32 v55, v7
	s_nop 0
	v_pk_mul_f32 v[52:53], v[54:55], v[52:53]
	s_nop 0
	v_pk_mul_f32 v[52:53], v[84:85], v[52:53]
	s_nop 0
	v_cvt_pk_bf16_f32 v139, v52, v53
	global_store_dwordx4 v[4:5], v[136:139], off offset:2048
	v_lshl_add_u64 v[4:5], v[4:5], 0, s[28:29]
	s_waitcnt vmcnt(7)
	v_lshlrev_b32_e32 v26, 16, v140
	v_and_b32_e32 v27, 0xffff0000, v140
	v_lshlrev_b32_e32 v24, 16, v56
	v_lshlrev_b32_e32 v20, 16, v88
	v_mul_f32_e32 v7, 0xbfb8aa3b, v20
	v_exp_f32_e32 v7, v7
	v_and_b32_e32 v21, 0xffff0000, v88
	v_lshlrev_b32_e32 v88, 16, v89
	v_and_b32_e32 v89, 0xffff0000, v89
	v_add_f32_e32 v7, 1.0, v7
	v_rcp_f32_e32 v22, v7
	v_mul_f32_e32 v7, 0xbfb8aa3b, v21
	v_exp_f32_e32 v7, v7
	v_and_b32_e32 v25, 0xffff0000, v56
	v_pk_mul_f32 v[24:25], v[26:27], v[24:25]
	v_add_f32_e32 v7, 1.0, v7
	v_rcp_f32_e32 v23, v7
	v_mul_f32_e32 v7, 0xbfb8aa3b, v88
	v_exp_f32_e32 v7, v7
	v_pk_mul_f32 v[20:21], v[22:23], v[20:21]
	s_nop 0
	v_pk_mul_f32 v[20:21], v[24:25], v[20:21]
	v_add_f32_e32 v7, 1.0, v7
	v_rcp_f32_e32 v56, v7
	v_mul_f32_e32 v7, 0xbfb8aa3b, v89
	v_exp_f32_e32 v7, v7
	v_cvt_pk_bf16_f32 v140, v20, v21
	v_lshlrev_b32_e32 v20, 16, v57
	v_and_b32_e32 v21, 0xffff0000, v57
	v_add_f32_e32 v7, 1.0, v7
	v_rcp_f32_e32 v57, v7
	v_lshlrev_b32_e32 v22, 16, v141
	v_and_b32_e32 v23, 0xffff0000, v141
	v_pk_mul_f32 v[20:21], v[22:23], v[20:21]
	v_pk_mul_f32 v[56:57], v[56:57], v[88:89]
	v_lshlrev_b32_e32 v22, 16, v142
	v_pk_mul_f32 v[56:57], v[20:21], v[56:57]
	v_lshlrev_b32_e32 v20, 16, v58
	v_cvt_pk_bf16_f32 v141, v56, v57
	v_lshlrev_b32_e32 v56, 16, v90
	v_mul_f32_e32 v7, 0xbfb8aa3b, v56
	v_exp_f32_e32 v7, v7
	v_and_b32_e32 v57, 0xffff0000, v90
	v_and_b32_e32 v21, 0xffff0000, v58
	v_and_b32_e32 v23, 0xffff0000, v142
	v_add_f32_e32 v7, 1.0, v7
	v_rcp_f32_e32 v88, v7
	v_mul_f32_e32 v7, 0xbfb8aa3b, v57
	v_exp_f32_e32 v7, v7
	v_pk_mul_f32 v[20:21], v[22:23], v[20:21]
	v_lshlrev_b32_e32 v90, 16, v143
	v_add_f32_e32 v7, 1.0, v7
	v_rcp_f32_e32 v89, v7
	s_nop 0
	v_pk_mul_f32 v[56:57], v[88:89], v[56:57]
	s_nop 0
	v_pk_mul_f32 v[56:57], v[20:21], v[56:57]
	v_lshlrev_b32_e32 v88, 16, v59
	v_cvt_pk_bf16_f32 v142, v56, v57
	v_lshlrev_b32_e32 v56, 16, v91
	v_mul_f32_e32 v7, 0xbfb8aa3b, v56
	v_exp_f32_e32 v7, v7
	v_and_b32_e32 v57, 0xffff0000, v91
	v_and_b32_e32 v89, 0xffff0000, v59
	v_and_b32_e32 v91, 0xffff0000, v143
	v_add_f32_e32 v7, 1.0, v7
	v_rcp_f32_e32 v58, v7
	v_mul_f32_e32 v7, 0xbfb8aa3b, v57
	v_exp_f32_e32 v7, v7
	v_pk_mul_f32 v[88:89], v[90:91], v[88:89]
	v_add_f32_e32 v7, 1.0, v7
	v_rcp_f32_e32 v59, v7
	s_nop 0
	v_pk_mul_f32 v[56:57], v[58:59], v[56:57]
	s_nop 0
	v_pk_mul_f32 v[56:57], v[88:89], v[56:57]
	s_nop 0
	v_cvt_pk_bf16_f32 v143, v56, v57
	global_store_dwordx4 v[4:5], v[140:143], off offset:2048
	s_branch .LBB0_305

.LBB0_326:
	s_lshl_b32 s0, s23, 4
	s_ashr_i32 s50, s28, 6
	s_and_b32 s49, s0, 0xffffffc0
	s_cmpk_lt_i32 s49, 0x2000
	s_movk_i32 s1, 0xf800
	s_cselect_b32 s1, 0xffffff00, s1
	s_movk_i32 s23, 0x800
	v_and_b32_e32 v0, 63, v156
	s_cselect_b32 s51, 0x100, s23
	s_and_b32 s54, s1, s0
	s_and_b32 s48, s50, -2
	v_lshlrev_b32_e32 v157, 3, v0
	v_and_b32_e32 v155, 31, v156
	v_bfe_u32 v154, v156, 5, 1
	s_cmp_lt_i32 s55, 2
	s_mov_b64 s[0:1], -1
	s_cbranch_scc1 .LBB0_350
	s_cmp_gt_i32 s55, 2
	s_cbranch_scc0 .LBB0_338
	s_sub_i32 s60, s49, s54
	v_lshlrev_b32_e32 v0, 4, v155
	s_add_i32 s23, s60, -8
	v_add_u32_e32 v14, 0, v0
	v_lshl_add_u64 v[16:17], s[24:25], 0, v[0:1]
	v_ashrrev_i32_e32 v227, 5, v156
	v_add_u32_e32 v228, s23, v227
	v_mad_u32_u24 v226, v227, s69, v14
	v_add_u32_e32 v232, s54, v228
	v_mad_i64_i32 v[230:231], s[62:63], v232, s77, v[16:17]
	v_mov_b32_e32 v206, 0
	v_mov_b32_e32 v207, 0
	v_mov_b32_e32 v208, 0
	v_mov_b32_e32 v209, 0
	v_cmp_gt_u32_e32 vcc, s51, v228
	s_and_saveexec_b64 s[30:31], vcc
	global_load_dwordx4 v[206:209], v[230:231], off offset:1536
	s_mov_b64 exec, s[30:31]
	v_add_co_u32_e32 v230, vcc, 0x28000, v230
	s_nop 1
	v_addc_co_u32_e32 v231, vcc, 0, v231, vcc
	v_mov_b32_e32 v210, 0
	v_mov_b32_e32 v211, 0
	v_mov_b32_e32 v212, 0
	v_mov_b32_e32 v213, 0
	v_add_u32_e32 v229, 16, v228
	v_cmp_gt_u32_e32 vcc, s51, v229
	s_and_saveexec_b64 s[30:31], vcc
	global_load_dwordx4 v[210:213], v[230:231], off offset:1536
	s_mov_b64 exec, s[30:31]
	v_add_co_u32_e32 v230, vcc, 0x28000, v230
	s_nop 1
	v_addc_co_u32_e32 v231, vcc, 0, v231, vcc
	v_mov_b32_e32 v214, 0
	v_mov_b32_e32 v215, 0
	v_mov_b32_e32 v216, 0
	v_mov_b32_e32 v217, 0
	v_add_u32_e32 v229, 32, v228
	v_cmp_gt_u32_e32 vcc, s51, v229
	s_and_saveexec_b64 s[30:31], vcc
	global_load_dwordx4 v[214:217], v[230:231], off offset:1536
	s_mov_b64 exec, s[30:31]
	v_add_co_u32_e32 v230, vcc, 0x28000, v230
	s_nop 1
	v_addc_co_u32_e32 v231, vcc, 0, v231, vcc
	v_mov_b32_e32 v218, 0
	v_mov_b32_e32 v219, 0
	v_mov_b32_e32 v220, 0
	v_mov_b32_e32 v221, 0
	v_add_u32_e32 v229, 48, v228
	v_cmp_gt_u32_e32 vcc, s51, v229
	s_and_saveexec_b64 s[30:31], vcc
	global_load_dwordx4 v[218:221], v[230:231], off offset:1536
	s_mov_b64 exec, s[30:31]
	v_add_co_u32_e32 v230, vcc, 0x28000, v230
	s_nop 1
	v_addc_co_u32_e32 v231, vcc, 0, v231, vcc
	v_mov_b32_e32 v222, 0
	v_mov_b32_e32 v223, 0
	v_mov_b32_e32 v224, 0
	v_mov_b32_e32 v225, 0
	v_add_u32_e32 v229, 64, v228
	v_cmp_gt_u32_e32 vcc, s51, v229
	s_and_saveexec_b64 s[30:31], vcc
	global_load_dwordx4 v[222:225], v[230:231], off offset:1536
	s_mov_b64 exec, s[30:31]
	v_cmp_gt_i32_e32 vcc, 64, v156
	s_and_saveexec_b64 s[0:1], vcc
	s_cbranch_execz .LBB0_330
	v_lshlrev_b32_e32 v10, 2, v156
	v_ashrrev_i32_e32 v11, 31, v10
	v_lshl_add_u64 v[10:11], v[10:11], 2, s[40:41]
	global_load_dwordx4 v[196:199], v[10:11], off offset:3072
	v_lshl_add_u32 v233, v156, 4, 0
	v_add_u32_e32 v233, 0x13000, v233
.LBB0_330:
	s_or_b64 exec, exec, s[0:1]
	s_add_i32 s0, s45, s48
	s_ashr_i32 s1, s0, 31
	s_lshl_b64 s[0:1], s[0:1], 14
	s_add_u32 s0, s38, s0
	s_addc_u32 s1, s39, s1
	v_lshlrev_b32_e32 v0, 1, v157
	v_lshl_add_u64 v[10:11], s[0:1], 0, v[0:1]
	s_movk_i32 s23, 0x4000
	v_add_co_u32_e32 v12, vcc, s23, v10
	s_nop 1
	v_addc_co_u32_e32 v13, vcc, 0, v11, vcc
	global_load_dwordx4 v[2:5], v0, s[0:1]
	global_load_dwordx4 v[142:145], v0, s[0:1] offset:1024
	global_load_dwordx4 v[6:9], v[12:13], off
	global_load_dwordx4 v[146:149], v[12:13], off offset:1024
	global_load_dwordx4 v[138:141], v0, s[0:1] offset:2048
	global_load_dwordx4 v[122:125], v0, s[0:1] offset:3072
	global_load_dwordx4 v[150:153], v[12:13], off offset:2048
	global_load_dwordx4 v[126:129], v[12:13], off offset:3072
	v_add_co_u32_e32 v12, vcc, 0x1000, v10
	s_nop 1
	v_addc_co_u32_e32 v13, vcc, 0, v11, vcc
	v_add_co_u32_e32 v14, vcc, 0x5000, v10
	s_nop 1
	v_addc_co_u32_e32 v15, vcc, 0, v11, vcc
	global_load_dwordx4 v[130:133], v[12:13], off
	global_load_dwordx4 v[110:113], v[12:13], off offset:1024
	global_load_dwordx4 v[134:137], v[14:15], off
	global_load_dwordx4 v[114:117], v[14:15], off offset:1024
	global_load_dwordx4 v[106:109], v[12:13], off offset:2048
	global_load_dwordx4 v[90:93], v[12:13], off offset:3072
	global_load_dwordx4 v[118:121], v[14:15], off offset:2048
	global_load_dwordx4 v[94:97], v[14:15], off offset:3072
	v_add_co_u32_e32 v12, vcc, 0x2000, v10
	s_nop 1
	v_addc_co_u32_e32 v13, vcc, 0, v11, vcc
	v_add_co_u32_e32 v14, vcc, 0x6000, v10
	s_nop 1
	v_addc_co_u32_e32 v15, vcc, 0, v11, vcc
	global_load_dwordx4 v[98:101], v[12:13], off
	global_load_dwordx4 v[78:81], v[12:13], off offset:1024
	global_load_dwordx4 v[102:105], v[14:15], off
	global_load_dwordx4 v[82:85], v[14:15], off offset:1024
	global_load_dwordx4 v[74:77], v[12:13], off offset:2048
	global_load_dwordx4 v[58:61], v[12:13], off offset:3072
	global_load_dwordx4 v[86:89], v[14:15], off offset:2048
	global_load_dwordx4 v[62:65], v[14:15], off offset:3072
	v_add_co_u32_e32 v12, vcc, 0x3000, v10
	s_nop 1
	v_addc_co_u32_e32 v13, vcc, 0, v11, vcc
	v_add_co_u32_e32 v10, vcc, 0x7000, v10
	s_nop 1
	v_addc_co_u32_e32 v11, vcc, 0, v11, vcc
	global_load_dwordx4 v[66:69], v[12:13], off
	global_load_dwordx4 v[50:53], v[12:13], off offset:1024
	global_load_dwordx4 v[70:73], v[10:11], off
	global_load_dwordx4 v[54:57], v[10:11], off offset:1024
	global_load_dwordx4 v[46:49], v[12:13], off offset:2048
	global_load_dwordx4 v[38:41], v[12:13], off offset:3072
	global_load_dwordx4 v[42:45], v[10:11], off offset:2048
	global_load_dwordx4 v[34:37], v[10:11], off offset:3072
	s_barrier
	s_waitcnt vmcnt(32)
	ds_write_b128 v226, v[206:209]
	ds_write_b128 v226, v[210:213] offset:8448
	ds_write_b128 v226, v[214:217] offset:16896
	ds_write_b128 v226, v[218:221] offset:25344
	ds_write_b128 v226, v[222:225] offset:33792
	v_cmp_gt_i32_e32 vcc, 64, v156
	s_and_saveexec_b64 s[30:31], vcc
	ds_write_b128 v233, v[196:199]
	s_mov_b64 exec, s[30:31]
.LBB0_335:
	s_lshl_b32 s23, s50, 5
	s_and_b32 s0, s23, 32
	v_or_b32_e32 v0, s60, v155
	v_or_b32_e32 v0, s0, v0
	v_add_u32_e32 v10, 8, v0
	v_min_i32_e32 v10, s51, v10
	v_max_i32_e32 v0, 8, v0
	v_sub_u32_e32 v0, v10, v0
	v_add_u32_e32 v0, 8, v0
	v_cvt_f32_i32_e32 v0, v0
	s_lshl_b32 s1, s50, 6
	s_and_b32 s1, s1, 0xffffff80
	v_readlane_b32 s62, v255, 20
	v_div_scale_f32 v10, s[28:29], v0, v0, 1.0
	v_rcp_f32_e32 v11, v10
	s_waitcnt lgkmcnt(0)
	s_barrier
	v_fma_f32 v12, -v10, v11, 1.0
	v_fmac_f32_e32 v11, v12, v11
	v_div_scale_f32 v12, vcc, 1.0, v0, 1.0
	v_mul_f32_e32 v13, v12, v11
	v_fma_f32 v14, -v10, v13, v12
	v_fmac_f32_e32 v13, v14, v11
	v_fma_f32 v10, -v10, v13, v12
	v_div_fmas_f32 v10, v10, v11, v13
	v_or_b32_e32 v13, s0, v155
	v_mov_b32_e32 v14, s1
	v_div_fixup_f32 v10, v10, v0, 1.0
	v_mul_u32_u24_e32 v0, 0x210, v13
	v_lshlrev_b32_e32 v12, 4, v154
	v_mad_u32_u24 v13, v13, s69, v14
	v_mov_b32_e32 v11, v10
	v_add3_u32 v13, v13, v12, 0
	s_mov_b32 s1, 0

.LBB0_338:
	s_and_b64 vcc, exec, s[0:1]
	s_cbranch_vccz .LBB0_349
	s_sub_i32 s60, s49, s54
	v_lshlrev_b32_e32 v0, 4, v155
	s_add_i32 s23, s60, -4
	v_add_u32_e32 v14, 0, v0
	v_lshl_add_u64 v[16:17], s[24:25], 0, v[0:1]
	v_ashrrev_i32_e32 v227, 5, v156
	v_add_u32_e32 v228, s23, v227
	v_mad_u32_u24 v226, v227, s69, v14
	v_add_u32_e32 v232, s54, v228
	v_mad_i64_i32 v[230:231], s[62:63], v232, s77, v[16:17]
	v_mov_b32_e32 v206, 0
	v_mov_b32_e32 v207, 0
	v_mov_b32_e32 v208, 0
	v_mov_b32_e32 v209, 0
	v_cmp_gt_u32_e32 vcc, s51, v228
	s_and_saveexec_b64 s[30:31], vcc
	global_load_dwordx4 v[206:209], v[230:231], off offset:1024
	s_mov_b64 exec, s[30:31]
	v_add_co_u32_e32 v230, vcc, 0x28000, v230
	s_nop 1
	v_addc_co_u32_e32 v231, vcc, 0, v231, vcc
	v_mov_b32_e32 v210, 0
	v_mov_b32_e32 v211, 0
	v_mov_b32_e32 v212, 0
	v_mov_b32_e32 v213, 0
	v_add_u32_e32 v229, 16, v228
	v_cmp_gt_u32_e32 vcc, s51, v229
	s_and_saveexec_b64 s[30:31], vcc
	global_load_dwordx4 v[210:213], v[230:231], off offset:1024
	s_mov_b64 exec, s[30:31]
	v_add_co_u32_e32 v230, vcc, 0x28000, v230
	s_nop 1
	v_addc_co_u32_e32 v231, vcc, 0, v231, vcc
	v_mov_b32_e32 v214, 0
	v_mov_b32_e32 v215, 0
	v_mov_b32_e32 v216, 0
	v_mov_b32_e32 v217, 0
	v_add_u32_e32 v229, 32, v228
	v_cmp_gt_u32_e32 vcc, s51, v229
	s_and_saveexec_b64 s[30:31], vcc
	global_load_dwordx4 v[214:217], v[230:231], off offset:1024
	s_mov_b64 exec, s[30:31]
	v_add_co_u32_e32 v230, vcc, 0x28000, v230
	s_nop 1
	v_addc_co_u32_e32 v231, vcc, 0, v231, vcc
	v_mov_b32_e32 v218, 0
	v_mov_b32_e32 v219, 0
	v_mov_b32_e32 v220, 0
	v_mov_b32_e32 v221, 0
	v_add_u32_e32 v229, 48, v228
	v_cmp_gt_u32_e32 vcc, s51, v229
	s_and_saveexec_b64 s[30:31], vcc
	global_load_dwordx4 v[218:221], v[230:231], off offset:1024
	s_mov_b64 exec, s[30:31]
	v_add_co_u32_e32 v230, vcc, 0x28000, v230
	s_nop 1
	v_addc_co_u32_e32 v231, vcc, 0, v231, vcc
	v_mov_b32_e32 v222, 0
	v_mov_b32_e32 v223, 0
	v_mov_b32_e32 v224, 0
	v_mov_b32_e32 v225, 0
	v_add_u32_e32 v229, 64, v228
	v_cmp_gt_u32_e32 vcc, s51, v229
	s_and_saveexec_b64 s[30:31], vcc
	global_load_dwordx4 v[222:225], v[230:231], off offset:1024
	s_mov_b64 exec, s[30:31]
	v_cmp_gt_i32_e32 vcc, 64, v156
	s_and_saveexec_b64 s[0:1], vcc
	s_cbranch_execz .LBB0_341
	v_lshlrev_b32_e32 v10, 2, v156
	v_ashrrev_i32_e32 v11, 31, v10
	v_lshl_add_u64 v[10:11], v[10:11], 2, s[40:41]
	global_load_dwordx4 v[196:199], v[10:11], off offset:2048
	v_lshl_add_u32 v233, v156, 4, 0
	v_add_u32_e32 v233, 0x13000, v233
.LBB0_341:
	s_or_b64 exec, exec, s[0:1]
	s_add_i32 s0, s46, s48
	s_ashr_i32 s1, s0, 31
	s_lshl_b64 s[0:1], s[0:1], 14
	s_add_u32 s0, s38, s0
	s_addc_u32 s1, s39, s1
	v_lshlrev_b32_e32 v0, 1, v157
	s_nop 0
	v_lshl_add_u64 v[10:11], s[0:1], 0, v[0:1]
	s_movk_i32 s23, 0x4000
	v_add_co_u32_e32 v12, vcc, s23, v10
	s_nop 1
	v_addc_co_u32_e32 v13, vcc, 0, v11, vcc
	global_load_dwordx4 v[2:5], v0, s[0:1]
	global_load_dwordx4 v[142:145], v0, s[0:1] offset:1024
	global_load_dwordx4 v[6:9], v[12:13], off
	global_load_dwordx4 v[146:149], v[12:13], off offset:1024
	global_load_dwordx4 v[138:141], v0, s[0:1] offset:2048
	global_load_dwordx4 v[122:125], v0, s[0:1] offset:3072
	global_load_dwordx4 v[150:153], v[12:13], off offset:2048
	global_load_dwordx4 v[126:129], v[12:13], off offset:3072
	v_add_co_u32_e32 v12, vcc, 0x1000, v10
	s_nop 1
	v_addc_co_u32_e32 v13, vcc, 0, v11, vcc
	v_add_co_u32_e32 v14, vcc, 0x5000, v10
	s_nop 1
	v_addc_co_u32_e32 v15, vcc, 0, v11, vcc
	global_load_dwordx4 v[130:133], v[12:13], off
	global_load_dwordx4 v[110:113], v[12:13], off offset:1024
	global_load_dwordx4 v[134:137], v[14:15], off
	global_load_dwordx4 v[114:117], v[14:15], off offset:1024
	global_load_dwordx4 v[106:109], v[12:13], off offset:2048
	global_load_dwordx4 v[90:93], v[12:13], off offset:3072
	global_load_dwordx4 v[118:121], v[14:15], off offset:2048
	global_load_dwordx4 v[94:97], v[14:15], off offset:3072
	v_add_co_u32_e32 v12, vcc, 0x2000, v10
	s_nop 1
	v_addc_co_u32_e32 v13, vcc, 0, v11, vcc
	v_add_co_u32_e32 v14, vcc, 0x6000, v10
	s_nop 1
	v_addc_co_u32_e32 v15, vcc, 0, v11, vcc
	global_load_dwordx4 v[98:101], v[12:13], off
	global_load_dwordx4 v[78:81], v[12:13], off offset:1024
	global_load_dwordx4 v[102:105], v[14:15], off
	global_load_dwordx4 v[82:85], v[14:15], off offset:1024
	global_load_dwordx4 v[74:77], v[12:13], off offset:2048
	global_load_dwordx4 v[58:61], v[12:13], off offset:3072
	global_load_dwordx4 v[86:89], v[14:15], off offset:2048
	global_load_dwordx4 v[62:65], v[14:15], off offset:3072
	v_add_co_u32_e32 v12, vcc, 0x3000, v10
	s_nop 1
	v_addc_co_u32_e32 v13, vcc, 0, v11, vcc
	v_add_co_u32_e32 v10, vcc, 0x7000, v10
	s_nop 1
	v_addc_co_u32_e32 v11, vcc, 0, v11, vcc
	global_load_dwordx4 v[66:69], v[12:13], off
	global_load_dwordx4 v[46:49], v[12:13], off offset:1024
	global_load_dwordx4 v[70:73], v[10:11], off
	global_load_dwordx4 v[50:53], v[10:11], off offset:1024
	global_load_dwordx4 v[42:45], v[12:13], off offset:2048
	global_load_dwordx4 v[38:41], v[12:13], off offset:3072
	global_load_dwordx4 v[54:57], v[10:11], off offset:2048
	global_load_dwordx4 v[34:37], v[10:11], off offset:3072
	s_barrier
	s_waitcnt vmcnt(32)
	ds_write_b128 v226, v[206:209]
	ds_write_b128 v226, v[210:213] offset:8448
	ds_write_b128 v226, v[214:217] offset:16896
	ds_write_b128 v226, v[218:221] offset:25344
	ds_write_b128 v226, v[222:225] offset:33792
	v_cmp_gt_i32_e32 vcc, 64, v156
	s_and_saveexec_b64 s[30:31], vcc
	ds_write_b128 v233, v[196:199]
	s_mov_b64 exec, s[30:31]
.LBB0_346:
	s_lshl_b32 s23, s50, 5
	s_and_b32 s0, s23, 32
	v_or_b32_e32 v0, s60, v155
	v_or_b32_e32 v0, s0, v0
	v_add_u32_e32 v10, 4, v0
	v_min_i32_e32 v10, s51, v10
	v_max_i32_e32 v0, 4, v0
	v_sub_u32_e32 v0, v10, v0
	v_add_u32_e32 v0, 4, v0
	v_cvt_f32_i32_e32 v0, v0
	s_lshl_b32 s1, s50, 6
	s_and_b32 s1, s1, 0xffffff80
	v_readlane_b32 s62, v255, 20
	v_div_scale_f32 v10, s[28:29], v0, v0, 1.0
	v_rcp_f32_e32 v11, v10
	s_waitcnt lgkmcnt(0)
	s_barrier
	v_fma_f32 v12, -v10, v11, 1.0
	v_fmac_f32_e32 v11, v12, v11
	v_div_scale_f32 v12, vcc, 1.0, v0, 1.0
	v_mul_f32_e32 v13, v12, v11
	v_fma_f32 v14, -v10, v13, v12
	v_fmac_f32_e32 v13, v14, v11
	v_fma_f32 v10, -v10, v13, v12
	v_div_fmas_f32 v10, v10, v11, v13
	v_or_b32_e32 v13, s0, v155
	v_mov_b32_e32 v14, s1
	v_div_fixup_f32 v10, v10, v0, 1.0
	v_mul_u32_u24_e32 v0, 0x210, v13
	v_lshlrev_b32_e32 v12, 4, v154
	v_mad_u32_u24 v13, v13, s69, v14
	v_mov_b32_e32 v11, v10
	v_add3_u32 v13, v13, v12, 0
	s_mov_b32 s1, 0

.LBB0_350:
	s_andn2_b64 vcc, exec, s[0:1]
	s_cbranch_vccnz .LBB0_320
	s_mov_b64 s[28:29], -1
	s_cmp_eq_u32 s55, 1
	v_cmp_gt_i32_e64 s[0:1], 64, v156
	v_lshlrev_b32_e32 v0, 1, v157
	s_cbranch_scc1 .LBB0_362
	s_sub_i32 s55, s49, s54
	v_lshlrev_b32_e32 v10, 4, v155
	v_mov_b32_e32 v11, v1
	s_add_i32 s23, s55, -1
	v_lshl_add_u64 v[14:15], s[24:25], 0, v[10:11]
	v_add_u32_e32 v16, 0, v10
	v_ashrrev_i32_e32 v227, 5, v156
	v_add_u32_e32 v228, s23, v227
	v_mad_u32_u24 v226, v227, s69, v16
	v_add_u32_e32 v232, s54, v228
	v_mad_i64_i32 v[230:231], s[62:63], v232, s77, v[14:15]
	v_mov_b32_e32 v206, 0
	v_mov_b32_e32 v207, 0
	v_mov_b32_e32 v208, 0
	v_mov_b32_e32 v209, 0
	v_cmp_gt_u32_e32 vcc, s51, v228
	s_and_saveexec_b64 s[30:31], vcc
	global_load_dwordx4 v[206:209], v[230:231], off
	s_mov_b64 exec, s[30:31]
	v_add_co_u32_e32 v230, vcc, 0x28000, v230
	s_nop 1
	v_addc_co_u32_e32 v231, vcc, 0, v231, vcc
	v_mov_b32_e32 v210, 0
	v_mov_b32_e32 v211, 0
	v_mov_b32_e32 v212, 0
	v_mov_b32_e32 v213, 0
	v_add_u32_e32 v229, 16, v228
	v_cmp_gt_u32_e32 vcc, s51, v229
	s_and_saveexec_b64 s[30:31], vcc
	global_load_dwordx4 v[210:213], v[230:231], off
	s_mov_b64 exec, s[30:31]
	v_add_co_u32_e32 v230, vcc, 0x28000, v230
	s_nop 1
	v_addc_co_u32_e32 v231, vcc, 0, v231, vcc
	v_mov_b32_e32 v214, 0
	v_mov_b32_e32 v215, 0
	v_mov_b32_e32 v216, 0
	v_mov_b32_e32 v217, 0
	v_add_u32_e32 v229, 32, v228
	v_cmp_gt_u32_e32 vcc, s51, v229
	s_and_saveexec_b64 s[30:31], vcc
	global_load_dwordx4 v[214:217], v[230:231], off
	s_mov_b64 exec, s[30:31]
	v_add_co_u32_e32 v230, vcc, 0x28000, v230
	s_nop 1
	v_addc_co_u32_e32 v231, vcc, 0, v231, vcc
	v_mov_b32_e32 v218, 0
	v_mov_b32_e32 v219, 0
	v_mov_b32_e32 v220, 0
	v_mov_b32_e32 v221, 0
	v_add_u32_e32 v229, 48, v228
	v_cmp_gt_u32_e32 vcc, s51, v229
	s_and_saveexec_b64 s[30:31], vcc
	global_load_dwordx4 v[218:221], v[230:231], off
	s_mov_b64 exec, s[30:31]
	v_add_co_u32_e32 v230, vcc, 0x28000, v230
	s_nop 1
	v_addc_co_u32_e32 v231, vcc, 0, v231, vcc
	v_mov_b32_e32 v222, 0
	v_mov_b32_e32 v223, 0
	v_mov_b32_e32 v224, 0
	v_mov_b32_e32 v225, 0
	v_add_u32_e32 v229, 64, v228
	v_cmp_gt_u32_e32 vcc, s51, v229
	s_and_saveexec_b64 s[30:31], vcc
	global_load_dwordx4 v[222:225], v[230:231], off
	s_mov_b64 exec, s[30:31]
	s_and_saveexec_b64 s[28:29], s[0:1]
	s_cbranch_execz .LBB0_354
	v_lshlrev_b32_e32 v10, 2, v156
	v_ashrrev_i32_e32 v11, 31, v10
	v_lshl_add_u64 v[10:11], v[10:11], 2, s[40:41]
	global_load_dwordx4 v[196:199], v[10:11], off
	v_lshl_add_u32 v233, v156, 4, 0
	v_add_u32_e32 v233, 0x13000, v233
.LBB0_354:
	s_or_b64 exec, exec, s[28:29]
	v_lshlrev_b32_e32 v0, 1, v157
	s_add_i32 s28, s48, s44
	s_ashr_i32 s29, s28, 31
	s_lshl_b64 s[28:29], s[28:29], 14
	s_add_u32 s28, s38, s28
	s_addc_u32 s29, s39, s29
	v_lshl_add_u64 v[10:11], s[28:29], 0, v[0:1]
	s_movk_i32 s23, 0x4000
	v_add_co_u32_e32 v12, vcc, s23, v10
	s_nop 1
	v_addc_co_u32_e32 v13, vcc, 0, v11, vcc
	global_load_dwordx4 v[2:5], v0, s[28:29]
	global_load_dwordx4 v[142:145], v0, s[28:29] offset:1024
	global_load_dwordx4 v[6:9], v[12:13], off
	global_load_dwordx4 v[146:149], v[12:13], off offset:1024
	global_load_dwordx4 v[138:141], v0, s[28:29] offset:2048
	global_load_dwordx4 v[122:125], v0, s[28:29] offset:3072
	global_load_dwordx4 v[150:153], v[12:13], off offset:2048
	global_load_dwordx4 v[126:129], v[12:13], off offset:3072
	v_add_co_u32_e32 v12, vcc, 0x1000, v10
	s_nop 1
	v_addc_co_u32_e32 v13, vcc, 0, v11, vcc
	v_add_co_u32_e32 v14, vcc, 0x5000, v10
	s_nop 1
	v_addc_co_u32_e32 v15, vcc, 0, v11, vcc
	global_load_dwordx4 v[130:133], v[12:13], off
	global_load_dwordx4 v[110:113], v[12:13], off offset:1024
	global_load_dwordx4 v[134:137], v[14:15], off
	global_load_dwordx4 v[114:117], v[14:15], off offset:1024
	global_load_dwordx4 v[106:109], v[12:13], off offset:2048
	global_load_dwordx4 v[90:93], v[12:13], off offset:3072
	global_load_dwordx4 v[118:121], v[14:15], off offset:2048
	global_load_dwordx4 v[94:97], v[14:15], off offset:3072
	v_add_co_u32_e32 v12, vcc, 0x2000, v10
	s_nop 1
	v_addc_co_u32_e32 v13, vcc, 0, v11, vcc
	v_add_co_u32_e32 v14, vcc, 0x6000, v10
	s_nop 1
	v_addc_co_u32_e32 v15, vcc, 0, v11, vcc
	global_load_dwordx4 v[98:101], v[12:13], off
	global_load_dwordx4 v[78:81], v[12:13], off offset:1024
	global_load_dwordx4 v[102:105], v[14:15], off
	global_load_dwordx4 v[82:85], v[14:15], off offset:1024
	global_load_dwordx4 v[74:77], v[12:13], off offset:2048
	global_load_dwordx4 v[58:61], v[12:13], off offset:3072
	global_load_dwordx4 v[86:89], v[14:15], off offset:2048
	global_load_dwordx4 v[62:65], v[14:15], off offset:3072
	v_add_co_u32_e32 v12, vcc, 0x3000, v10
	s_nop 1
	v_addc_co_u32_e32 v13, vcc, 0, v11, vcc
	v_add_co_u32_e32 v10, vcc, 0x7000, v10
	s_nop 1
	v_addc_co_u32_e32 v11, vcc, 0, v11, vcc
	global_load_dwordx4 v[66:69], v[12:13], off
	global_load_dwordx4 v[50:53], v[12:13], off offset:1024
	global_load_dwordx4 v[70:73], v[10:11], off
	global_load_dwordx4 v[54:57], v[10:11], off offset:1024
	global_load_dwordx4 v[46:49], v[12:13], off offset:2048
	global_load_dwordx4 v[38:41], v[12:13], off offset:3072
	global_load_dwordx4 v[42:45], v[10:11], off offset:2048
	global_load_dwordx4 v[34:37], v[10:11], off offset:3072
	s_barrier
	s_waitcnt vmcnt(32)
	ds_write_b128 v226, v[206:209]
	ds_write_b128 v226, v[210:213] offset:8448
	ds_write_b128 v226, v[214:217] offset:16896
	ds_write_b128 v226, v[218:221] offset:25344
	ds_write_b128 v226, v[222:225] offset:33792
	v_cmp_gt_i32_e32 vcc, 64, v156
	s_and_saveexec_b64 s[30:31], vcc
	ds_write_b128 v233, v[196:199]
	s_mov_b64 exec, s[30:31]
.LBB0_359:
	s_lshl_b32 s23, s50, 5
	s_and_b32 s0, s23, 32
	v_or_b32_e32 v10, s55, v155
	v_or_b32_e32 v10, s0, v10
	v_add_u32_e32 v11, 1, v10
	v_min_i32_e32 v11, s51, v11
	v_max_i32_e32 v10, 1, v10
	v_sub_u32_e32 v10, v11, v10
	v_add_u32_e32 v10, 1, v10
	v_cvt_f32_i32_e32 v10, v10
	s_lshl_b32 s1, s50, 6
	s_and_b32 s1, s1, 0xffffff80
	v_readlane_b32 s62, v255, 20
	v_div_scale_f32 v11, s[28:29], v10, v10, 1.0
	v_rcp_f32_e32 v12, v11
	s_waitcnt lgkmcnt(0)
	s_barrier
	v_fma_f32 v13, -v11, v12, 1.0
	v_fmac_f32_e32 v12, v13, v12
	v_div_scale_f32 v13, vcc, 1.0, v10, 1.0
	v_mul_f32_e32 v14, v13, v12
	v_fma_f32 v15, -v11, v14, v13
	v_fmac_f32_e32 v14, v15, v12
	v_fma_f32 v11, -v11, v14, v13
	v_div_fmas_f32 v11, v11, v12, v14
	v_or_b32_e32 v14, s0, v155
	v_mov_b32_e32 v15, s1
	v_div_fixup_f32 v10, v11, v10, 1.0
	v_mul_u32_u24_e32 v12, 0x210, v14
	v_lshlrev_b32_e32 v13, 4, v154
	v_mad_u32_u24 v14, v14, s69, v15
	v_mov_b32_e32 v11, v10
	v_add3_u32 v14, v14, v13, 0
	s_mov_b32 s1, 0

.LBB0_362:
	s_and_b64 vcc, exec, s[28:29]
	s_cbranch_vccz .LBB0_320
	s_sub_i32 s55, s49, s54
	v_lshlrev_b32_e32 v0, 4, v155
	s_add_i32 s23, s55, -2
	v_add_u32_e32 v14, 0, v0
	v_lshl_add_u64 v[16:17], s[24:25], 0, v[0:1]
	v_ashrrev_i32_e32 v227, 5, v156
	v_add_u32_e32 v228, s23, v227
	v_mad_u32_u24 v226, v227, s69, v14
	v_add_u32_e32 v232, s54, v228
	v_mad_i64_i32 v[230:231], s[62:63], v232, s77, v[16:17]
	v_mov_b32_e32 v206, 0
	v_mov_b32_e32 v207, 0
	v_mov_b32_e32 v208, 0
	v_mov_b32_e32 v209, 0
	v_cmp_gt_u32_e32 vcc, s51, v228
	s_and_saveexec_b64 s[30:31], vcc
	global_load_dwordx4 v[206:209], v[230:231], off offset:512
	s_mov_b64 exec, s[30:31]
	v_add_co_u32_e32 v230, vcc, 0x28000, v230
	s_nop 1
	v_addc_co_u32_e32 v231, vcc, 0, v231, vcc
	v_mov_b32_e32 v210, 0
	v_mov_b32_e32 v211, 0
	v_mov_b32_e32 v212, 0
	v_mov_b32_e32 v213, 0
	v_add_u32_e32 v229, 16, v228
	v_cmp_gt_u32_e32 vcc, s51, v229
	s_and_saveexec_b64 s[30:31], vcc
	global_load_dwordx4 v[210:213], v[230:231], off offset:512
	s_mov_b64 exec, s[30:31]
	v_add_co_u32_e32 v230, vcc, 0x28000, v230
	s_nop 1
	v_addc_co_u32_e32 v231, vcc, 0, v231, vcc
	v_mov_b32_e32 v214, 0
	v_mov_b32_e32 v215, 0
	v_mov_b32_e32 v216, 0
	v_mov_b32_e32 v217, 0
	v_add_u32_e32 v229, 32, v228
	v_cmp_gt_u32_e32 vcc, s51, v229
	s_and_saveexec_b64 s[30:31], vcc
	global_load_dwordx4 v[214:217], v[230:231], off offset:512
	s_mov_b64 exec, s[30:31]
	v_add_co_u32_e32 v230, vcc, 0x28000, v230
	s_nop 1
	v_addc_co_u32_e32 v231, vcc, 0, v231, vcc
	v_mov_b32_e32 v218, 0
	v_mov_b32_e32 v219, 0
	v_mov_b32_e32 v220, 0
	v_mov_b32_e32 v221, 0
	v_add_u32_e32 v229, 48, v228
	v_cmp_gt_u32_e32 vcc, s51, v229
	s_and_saveexec_b64 s[30:31], vcc
	global_load_dwordx4 v[218:221], v[230:231], off offset:512
	s_mov_b64 exec, s[30:31]
	v_add_co_u32_e32 v230, vcc, 0x28000, v230
	s_nop 1
	v_addc_co_u32_e32 v231, vcc, 0, v231, vcc
	v_mov_b32_e32 v222, 0
	v_mov_b32_e32 v223, 0
	v_mov_b32_e32 v224, 0
	v_mov_b32_e32 v225, 0
	v_add_u32_e32 v229, 64, v228
	v_cmp_gt_u32_e32 vcc, s51, v229
	s_and_saveexec_b64 s[30:31], vcc
	global_load_dwordx4 v[222:225], v[230:231], off offset:512
	s_mov_b64 exec, s[30:31]
	v_cmp_gt_i32_e32 vcc, 64, v156
	s_and_saveexec_b64 s[0:1], vcc
	s_cbranch_execz .LBB0_365
	v_lshlrev_b32_e32 v10, 2, v156
	v_ashrrev_i32_e32 v11, 31, v10
	v_lshl_add_u64 v[10:11], v[10:11], 2, s[40:41]
	global_load_dwordx4 v[196:199], v[10:11], off offset:1024
	v_lshl_add_u32 v233, v156, 4, 0
	v_add_u32_e32 v233, 0x13000, v233
.LBB0_365:
	s_or_b64 exec, exec, s[0:1]
	v_lshlrev_b32_e32 v0, 1, v157
	s_add_i32 s0, s47, s48
	s_ashr_i32 s1, s0, 31
	s_lshl_b64 s[0:1], s[0:1], 14
	s_add_u32 s0, s38, s0
	s_addc_u32 s1, s39, s1
	s_nop 3
	v_lshl_add_u64 v[10:11], s[0:1], 0, v[0:1]
	s_movk_i32 s23, 0x4000
	v_add_co_u32_e32 v12, vcc, s23, v10
	s_nop 1
	v_addc_co_u32_e32 v13, vcc, 0, v11, vcc
	global_load_dwordx4 v[2:5], v0, s[0:1]
	global_load_dwordx4 v[142:145], v0, s[0:1] offset:1024
	global_load_dwordx4 v[6:9], v[12:13], off
	global_load_dwordx4 v[146:149], v[12:13], off offset:1024
	global_load_dwordx4 v[138:141], v0, s[0:1] offset:2048
	global_load_dwordx4 v[122:125], v0, s[0:1] offset:3072
	global_load_dwordx4 v[150:153], v[12:13], off offset:2048
	global_load_dwordx4 v[126:129], v[12:13], off offset:3072
	v_add_co_u32_e32 v12, vcc, 0x1000, v10
	s_nop 1
	v_addc_co_u32_e32 v13, vcc, 0, v11, vcc
	v_add_co_u32_e32 v14, vcc, 0x5000, v10
	s_nop 1
	v_addc_co_u32_e32 v15, vcc, 0, v11, vcc
	global_load_dwordx4 v[130:133], v[12:13], off
	global_load_dwordx4 v[110:113], v[12:13], off offset:1024
	global_load_dwordx4 v[134:137], v[14:15], off
	global_load_dwordx4 v[114:117], v[14:15], off offset:1024
	global_load_dwordx4 v[106:109], v[12:13], off offset:2048
	global_load_dwordx4 v[90:93], v[12:13], off offset:3072
	global_load_dwordx4 v[118:121], v[14:15], off offset:2048
	global_load_dwordx4 v[94:97], v[14:15], off offset:3072
	v_add_co_u32_e32 v12, vcc, 0x2000, v10
	s_nop 1
	v_addc_co_u32_e32 v13, vcc, 0, v11, vcc
	v_add_co_u32_e32 v14, vcc, 0x6000, v10
	s_nop 1
	v_addc_co_u32_e32 v15, vcc, 0, v11, vcc
	global_load_dwordx4 v[98:101], v[12:13], off
	global_load_dwordx4 v[78:81], v[12:13], off offset:1024
	global_load_dwordx4 v[102:105], v[14:15], off
	global_load_dwordx4 v[82:85], v[14:15], off offset:1024
	global_load_dwordx4 v[74:77], v[12:13], off offset:2048
	global_load_dwordx4 v[58:61], v[12:13], off offset:3072
	global_load_dwordx4 v[86:89], v[14:15], off offset:2048
	global_load_dwordx4 v[62:65], v[14:15], off offset:3072
	v_add_co_u32_e32 v12, vcc, 0x3000, v10
	s_nop 1
	v_addc_co_u32_e32 v13, vcc, 0, v11, vcc
	v_add_co_u32_e32 v10, vcc, 0x7000, v10
	s_nop 1
	v_addc_co_u32_e32 v11, vcc, 0, v11, vcc
	global_load_dwordx4 v[66:69], v[12:13], off
	global_load_dwordx4 v[46:49], v[12:13], off offset:1024
	global_load_dwordx4 v[70:73], v[10:11], off
	global_load_dwordx4 v[50:53], v[10:11], off offset:1024
	global_load_dwordx4 v[42:45], v[12:13], off offset:2048
	global_load_dwordx4 v[38:41], v[12:13], off offset:3072
	global_load_dwordx4 v[54:57], v[10:11], off offset:2048
	global_load_dwordx4 v[34:37], v[10:11], off offset:3072
	s_barrier
	s_waitcnt vmcnt(32)
	ds_write_b128 v226, v[206:209]
	ds_write_b128 v226, v[210:213] offset:8448
	ds_write_b128 v226, v[214:217] offset:16896
	ds_write_b128 v226, v[218:221] offset:25344
	ds_write_b128 v226, v[222:225] offset:33792
	v_cmp_gt_i32_e32 vcc, 64, v156
	s_and_saveexec_b64 s[30:31], vcc
	ds_write_b128 v233, v[196:199]
	s_mov_b64 exec, s[30:31]
.LBB0_370:
	s_lshl_b32 s23, s50, 5
	s_and_b32 s0, s23, 32
	v_or_b32_e32 v0, s55, v155
	v_or_b32_e32 v0, s0, v0
	v_add_u32_e32 v10, 2, v0
	v_min_i32_e32 v10, s51, v10
	v_max_i32_e32 v0, 2, v0
	v_sub_u32_e32 v0, v10, v0
	v_add_u32_e32 v0, 2, v0
	v_cvt_f32_i32_e32 v0, v0
	s_lshl_b32 s1, s50, 6
	s_and_b32 s1, s1, 0xffffff80
	v_readlane_b32 s62, v255, 20
	v_div_scale_f32 v10, s[28:29], v0, v0, 1.0
	v_rcp_f32_e32 v11, v10
	s_waitcnt lgkmcnt(0)
	s_barrier
	v_fma_f32 v12, -v10, v11, 1.0
	v_fmac_f32_e32 v11, v12, v11
	v_div_scale_f32 v12, vcc, 1.0, v0, 1.0
	v_mul_f32_e32 v13, v12, v11
	v_fma_f32 v14, -v10, v13, v12
	v_fmac_f32_e32 v13, v14, v11
	v_fma_f32 v10, -v10, v13, v12
	v_div_fmas_f32 v10, v10, v11, v13
	v_or_b32_e32 v13, s0, v155
	v_mov_b32_e32 v14, s1
	v_div_fixup_f32 v10, v10, v0, 1.0
	v_mul_u32_u24_e32 v0, 0x210, v13
	v_lshlrev_b32_e32 v12, 4, v154
	v_mad_u32_u24 v13, v13, s69, v14
	v_mov_b32_e32 v11, v10
	v_add3_u32 v13, v13, v12, 0
	s_mov_b32 s1, 0

.LBB0_379:
	s_lshl_b32 s0, s22, 4
	s_ashr_i32 s50, s23, 6
	s_and_b32 s49, s0, 0xffffffc0
	s_cmpk_lt_i32 s49, 0x2000
	s_movk_i32 s1, 0xf800
	s_cselect_b32 s1, 0xffffff00, s1
	s_movk_i32 s23, 0x800
	v_and_b32_e32 v0, 63, v156
	s_cselect_b32 s51, 0x100, s23
	s_and_b32 s54, s1, s0
	s_and_b32 s48, s50, -2
	v_lshlrev_b32_e32 v157, 3, v0
	v_and_b32_e32 v155, 31, v156
	v_bfe_u32 v154, v156, 5, 1
	s_cmp_lt_i32 s55, 2
	s_mov_b64 s[0:1], -1
	s_cbranch_scc1 .LBB0_403
	s_cmp_gt_i32 s55, 2
	s_cbranch_scc0 .LBB0_391
	s_add_i32 s0, s45, s48
	s_ashr_i32 s1, s0, 31
	s_lshl_b64 s[0:1], s[0:1], 14
	s_add_u32 s0, s38, s0
	s_addc_u32 s1, s39, s1
	v_lshlrev_b32_e32 v0, 1, v157
	v_lshl_add_u64 v[10:11], s[0:1], 0, v[0:1]
	s_movk_i32 s23, 0x4000
	v_add_co_u32_e32 v12, vcc, s23, v10
	s_nop 1
	v_addc_co_u32_e32 v13, vcc, 0, v11, vcc
	global_load_dwordx4 v[2:5], v0, s[0:1]
	global_load_dwordx4 v[142:145], v0, s[0:1] offset:1024
	global_load_dwordx4 v[6:9], v[12:13], off
	global_load_dwordx4 v[146:149], v[12:13], off offset:1024
	global_load_dwordx4 v[138:141], v0, s[0:1] offset:2048
	global_load_dwordx4 v[122:125], v0, s[0:1] offset:3072
	global_load_dwordx4 v[150:153], v[12:13], off offset:2048
	global_load_dwordx4 v[126:129], v[12:13], off offset:3072
	v_add_co_u32_e32 v12, vcc, 0x1000, v10
	s_nop 1
	v_addc_co_u32_e32 v13, vcc, 0, v11, vcc
	v_add_co_u32_e32 v14, vcc, 0x5000, v10
	s_nop 1
	v_addc_co_u32_e32 v15, vcc, 0, v11, vcc
	global_load_dwordx4 v[130:133], v[12:13], off
	global_load_dwordx4 v[110:113], v[12:13], off offset:1024
	global_load_dwordx4 v[134:137], v[14:15], off
	global_load_dwordx4 v[114:117], v[14:15], off offset:1024
	global_load_dwordx4 v[106:109], v[12:13], off offset:2048
	global_load_dwordx4 v[90:93], v[12:13], off offset:3072
	global_load_dwordx4 v[118:121], v[14:15], off offset:2048
	global_load_dwordx4 v[94:97], v[14:15], off offset:3072
	v_add_co_u32_e32 v12, vcc, 0x2000, v10
	s_nop 1
	v_addc_co_u32_e32 v13, vcc, 0, v11, vcc
	v_add_co_u32_e32 v14, vcc, 0x6000, v10
	s_nop 1
	v_addc_co_u32_e32 v15, vcc, 0, v11, vcc
	global_load_dwordx4 v[98:101], v[12:13], off
	global_load_dwordx4 v[78:81], v[12:13], off offset:1024
	global_load_dwordx4 v[102:105], v[14:15], off
	global_load_dwordx4 v[82:85], v[14:15], off offset:1024
	global_load_dwordx4 v[74:77], v[12:13], off offset:2048
	global_load_dwordx4 v[58:61], v[12:13], off offset:3072
	global_load_dwordx4 v[86:89], v[14:15], off offset:2048
	global_load_dwordx4 v[62:65], v[14:15], off offset:3072
	v_add_co_u32_e32 v12, vcc, 0x3000, v10
	s_nop 1
	v_addc_co_u32_e32 v13, vcc, 0, v11, vcc
	v_add_co_u32_e32 v10, vcc, 0x7000, v10
	s_nop 1
	v_addc_co_u32_e32 v11, vcc, 0, v11, vcc
	global_load_dwordx4 v[66:69], v[12:13], off
	global_load_dwordx4 v[50:53], v[12:13], off offset:1024
	global_load_dwordx4 v[70:73], v[10:11], off
	global_load_dwordx4 v[54:57], v[10:11], off offset:1024
	global_load_dwordx4 v[46:49], v[12:13], off offset:2048
	global_load_dwordx4 v[38:41], v[12:13], off offset:3072
	global_load_dwordx4 v[42:45], v[10:11], off offset:2048
	global_load_dwordx4 v[34:37], v[10:11], off offset:3072
	v_cmp_gt_i32_e32 vcc, 64, v156
	s_and_saveexec_b64 s[0:1], vcc
	s_cbranch_execz .LBB0_383
	v_lshlrev_b32_e32 v10, 2, v156
	v_ashrrev_i32_e32 v11, 31, v10
	v_lshl_add_u64 v[10:11], v[10:11], 2, s[40:41]
	global_load_dwordx4 v[196:199], v[10:11], off offset:3072
	v_lshl_add_u32 v233, v156, 4, 0
	v_add_u32_e32 v233, 0x13000, v233
.LBB0_383:
	s_or_b64 exec, exec, s[0:1]
	s_movk_i32 s0, 0xa00
	s_sub_i32 s60, s49, s54
	v_cmp_gt_i32_e32 vcc, s0, v156
	s_and_saveexec_b64 s[0:1], vcc
	s_cbranch_execz .LBB0_388
	v_lshlrev_b32_e32 v0, 4, v155
	s_add_i32 s23, s60, -8
	v_add_u32_e32 v14, 0, v0
	v_lshl_add_u64 v[16:17], s[24:25], 0, v[0:1]
	v_ashrrev_i32_e32 v227, 5, v156
	v_add_u32_e32 v228, s23, v227
	v_mad_u32_u24 v226, v227, s69, v14
	v_add_u32_e32 v232, s54, v228
	v_mad_i64_i32 v[230:231], s[62:63], v232, s77, v[16:17]
	v_mov_b32_e32 v206, 0
	v_mov_b32_e32 v207, 0
	v_mov_b32_e32 v208, 0
	v_mov_b32_e32 v209, 0
	v_cmp_gt_u32_e32 vcc, s51, v228
	s_and_saveexec_b64 s[30:31], vcc
	global_load_dwordx4 v[206:209], v[230:231], off offset:1536
	s_mov_b64 exec, s[30:31]
	v_add_co_u32_e32 v230, vcc, 0x28000, v230
	s_nop 1
	v_addc_co_u32_e32 v231, vcc, 0, v231, vcc
	v_mov_b32_e32 v210, 0
	v_mov_b32_e32 v211, 0
	v_mov_b32_e32 v212, 0
	v_mov_b32_e32 v213, 0
	v_add_u32_e32 v229, 16, v228
	v_cmp_gt_u32_e32 vcc, s51, v229
	s_and_saveexec_b64 s[30:31], vcc
	global_load_dwordx4 v[210:213], v[230:231], off offset:1536
	s_mov_b64 exec, s[30:31]
	v_add_co_u32_e32 v230, vcc, 0x28000, v230
	s_nop 1
	v_addc_co_u32_e32 v231, vcc, 0, v231, vcc
	v_mov_b32_e32 v214, 0
	v_mov_b32_e32 v215, 0
	v_mov_b32_e32 v216, 0
	v_mov_b32_e32 v217, 0
	v_add_u32_e32 v229, 32, v228
	v_cmp_gt_u32_e32 vcc, s51, v229
	s_and_saveexec_b64 s[30:31], vcc
	global_load_dwordx4 v[214:217], v[230:231], off offset:1536
	s_mov_b64 exec, s[30:31]
	v_add_co_u32_e32 v230, vcc, 0x28000, v230
	s_nop 1
	v_addc_co_u32_e32 v231, vcc, 0, v231, vcc
	v_mov_b32_e32 v218, 0
	v_mov_b32_e32 v219, 0
	v_mov_b32_e32 v220, 0
	v_mov_b32_e32 v221, 0
	v_add_u32_e32 v229, 48, v228
	v_cmp_gt_u32_e32 vcc, s51, v229
	s_and_saveexec_b64 s[30:31], vcc
	global_load_dwordx4 v[218:221], v[230:231], off offset:1536
	s_mov_b64 exec, s[30:31]
	v_add_co_u32_e32 v230, vcc, 0x28000, v230
	s_nop 1
	v_addc_co_u32_e32 v231, vcc, 0, v231, vcc
	v_mov_b32_e32 v222, 0
	v_mov_b32_e32 v223, 0
	v_mov_b32_e32 v224, 0
	v_mov_b32_e32 v225, 0
	v_add_u32_e32 v229, 64, v228
	v_cmp_gt_u32_e32 vcc, s51, v229
	s_and_saveexec_b64 s[30:31], vcc
	global_load_dwordx4 v[222:225], v[230:231], off offset:1536
	s_mov_b64 exec, s[30:31]
	s_barrier
	s_waitcnt vmcnt(0)
	ds_write_b128 v226, v[206:209]
	ds_write_b128 v226, v[210:213] offset:8448
	ds_write_b128 v226, v[214:217] offset:16896
	ds_write_b128 v226, v[218:221] offset:25344
	ds_write_b128 v226, v[222:225] offset:33792
	v_cmp_gt_i32_e32 vcc, 64, v156
	s_and_saveexec_b64 s[30:31], vcc
	ds_write_b128 v233, v[196:199]
	s_mov_b64 exec, s[30:31]

.LBB0_391:
	s_and_b64 vcc, exec, s[0:1]
	s_cbranch_vccz .LBB0_402
	s_add_i32 s0, s46, s48
	s_ashr_i32 s1, s0, 31
	s_lshl_b64 s[0:1], s[0:1], 14
	s_add_u32 s0, s38, s0
	s_addc_u32 s1, s39, s1
	v_lshlrev_b32_e32 v0, 1, v157
	s_nop 0
	v_lshl_add_u64 v[10:11], s[0:1], 0, v[0:1]
	s_movk_i32 s23, 0x4000
	v_add_co_u32_e32 v12, vcc, s23, v10
	s_nop 1
	v_addc_co_u32_e32 v13, vcc, 0, v11, vcc
	global_load_dwordx4 v[2:5], v0, s[0:1]
	global_load_dwordx4 v[142:145], v0, s[0:1] offset:1024
	global_load_dwordx4 v[6:9], v[12:13], off
	global_load_dwordx4 v[146:149], v[12:13], off offset:1024
	global_load_dwordx4 v[138:141], v0, s[0:1] offset:2048
	global_load_dwordx4 v[122:125], v0, s[0:1] offset:3072
	global_load_dwordx4 v[150:153], v[12:13], off offset:2048
	global_load_dwordx4 v[126:129], v[12:13], off offset:3072
	v_add_co_u32_e32 v12, vcc, 0x1000, v10
	s_nop 1
	v_addc_co_u32_e32 v13, vcc, 0, v11, vcc
	v_add_co_u32_e32 v14, vcc, 0x5000, v10
	s_nop 1
	v_addc_co_u32_e32 v15, vcc, 0, v11, vcc
	global_load_dwordx4 v[130:133], v[12:13], off
	global_load_dwordx4 v[110:113], v[12:13], off offset:1024
	global_load_dwordx4 v[134:137], v[14:15], off
	global_load_dwordx4 v[114:117], v[14:15], off offset:1024
	global_load_dwordx4 v[106:109], v[12:13], off offset:2048
	global_load_dwordx4 v[90:93], v[12:13], off offset:3072
	global_load_dwordx4 v[118:121], v[14:15], off offset:2048
	global_load_dwordx4 v[94:97], v[14:15], off offset:3072
	v_add_co_u32_e32 v12, vcc, 0x2000, v10
	s_nop 1
	v_addc_co_u32_e32 v13, vcc, 0, v11, vcc
	v_add_co_u32_e32 v14, vcc, 0x6000, v10
	s_nop 1
	v_addc_co_u32_e32 v15, vcc, 0, v11, vcc
	global_load_dwordx4 v[98:101], v[12:13], off
	global_load_dwordx4 v[78:81], v[12:13], off offset:1024
	global_load_dwordx4 v[102:105], v[14:15], off
	global_load_dwordx4 v[82:85], v[14:15], off offset:1024
	global_load_dwordx4 v[74:77], v[12:13], off offset:2048
	global_load_dwordx4 v[58:61], v[12:13], off offset:3072
	global_load_dwordx4 v[86:89], v[14:15], off offset:2048
	global_load_dwordx4 v[62:65], v[14:15], off offset:3072
	v_add_co_u32_e32 v12, vcc, 0x3000, v10
	s_nop 1
	v_addc_co_u32_e32 v13, vcc, 0, v11, vcc
	v_add_co_u32_e32 v10, vcc, 0x7000, v10
	s_nop 1
	v_addc_co_u32_e32 v11, vcc, 0, v11, vcc
	global_load_dwordx4 v[66:69], v[12:13], off
	global_load_dwordx4 v[46:49], v[12:13], off offset:1024
	global_load_dwordx4 v[70:73], v[10:11], off
	global_load_dwordx4 v[50:53], v[10:11], off offset:1024
	global_load_dwordx4 v[42:45], v[12:13], off offset:2048
	global_load_dwordx4 v[38:41], v[12:13], off offset:3072
	global_load_dwordx4 v[54:57], v[10:11], off offset:2048
	global_load_dwordx4 v[34:37], v[10:11], off offset:3072
	v_cmp_gt_i32_e32 vcc, 64, v156
	s_and_saveexec_b64 s[0:1], vcc
	s_cbranch_execz .LBB0_394
	v_lshlrev_b32_e32 v10, 2, v156
	v_ashrrev_i32_e32 v11, 31, v10
	v_lshl_add_u64 v[10:11], v[10:11], 2, s[40:41]
	global_load_dwordx4 v[196:199], v[10:11], off offset:2048
	v_lshl_add_u32 v233, v156, 4, 0
	v_add_u32_e32 v233, 0x13000, v233
.LBB0_394:
	s_or_b64 exec, exec, s[0:1]
	s_movk_i32 s0, 0x900
	s_sub_i32 s60, s49, s54
	v_cmp_gt_i32_e32 vcc, s0, v156
	s_and_saveexec_b64 s[0:1], vcc
	s_cbranch_execz .LBB0_399
	v_lshlrev_b32_e32 v0, 4, v155
	s_add_i32 s23, s60, -4
	v_add_u32_e32 v14, 0, v0
	v_lshl_add_u64 v[16:17], s[24:25], 0, v[0:1]
	v_ashrrev_i32_e32 v227, 5, v156
	v_add_u32_e32 v228, s23, v227
	v_mad_u32_u24 v226, v227, s69, v14
	v_add_u32_e32 v232, s54, v228
	v_mad_i64_i32 v[230:231], s[62:63], v232, s77, v[16:17]
	v_mov_b32_e32 v206, 0
	v_mov_b32_e32 v207, 0
	v_mov_b32_e32 v208, 0
	v_mov_b32_e32 v209, 0
	v_cmp_gt_u32_e32 vcc, s51, v228
	s_and_saveexec_b64 s[30:31], vcc
	global_load_dwordx4 v[206:209], v[230:231], off offset:1024
	s_mov_b64 exec, s[30:31]
	v_add_co_u32_e32 v230, vcc, 0x28000, v230
	s_nop 1
	v_addc_co_u32_e32 v231, vcc, 0, v231, vcc
	v_mov_b32_e32 v210, 0
	v_mov_b32_e32 v211, 0
	v_mov_b32_e32 v212, 0
	v_mov_b32_e32 v213, 0
	v_add_u32_e32 v229, 16, v228
	v_cmp_gt_u32_e32 vcc, s51, v229
	s_and_saveexec_b64 s[30:31], vcc
	global_load_dwordx4 v[210:213], v[230:231], off offset:1024
	s_mov_b64 exec, s[30:31]
	v_add_co_u32_e32 v230, vcc, 0x28000, v230
	s_nop 1
	v_addc_co_u32_e32 v231, vcc, 0, v231, vcc
	v_mov_b32_e32 v214, 0
	v_mov_b32_e32 v215, 0
	v_mov_b32_e32 v216, 0
	v_mov_b32_e32 v217, 0
	v_add_u32_e32 v229, 32, v228
	v_cmp_gt_u32_e32 vcc, s51, v229
	s_and_saveexec_b64 s[30:31], vcc
	global_load_dwordx4 v[214:217], v[230:231], off offset:1024
	s_mov_b64 exec, s[30:31]
	v_add_co_u32_e32 v230, vcc, 0x28000, v230
	s_nop 1
	v_addc_co_u32_e32 v231, vcc, 0, v231, vcc
	v_mov_b32_e32 v218, 0
	v_mov_b32_e32 v219, 0
	v_mov_b32_e32 v220, 0
	v_mov_b32_e32 v221, 0
	v_add_u32_e32 v229, 48, v228
	v_cmp_gt_u32_e32 vcc, s51, v229
	s_and_saveexec_b64 s[30:31], vcc
	global_load_dwordx4 v[218:221], v[230:231], off offset:1024
	s_mov_b64 exec, s[30:31]
	v_add_co_u32_e32 v230, vcc, 0x28000, v230
	s_nop 1
	v_addc_co_u32_e32 v231, vcc, 0, v231, vcc
	v_mov_b32_e32 v222, 0
	v_mov_b32_e32 v223, 0
	v_mov_b32_e32 v224, 0
	v_mov_b32_e32 v225, 0
	v_add_u32_e32 v229, 64, v228
	v_cmp_gt_u32_e32 vcc, s51, v229
	s_and_saveexec_b64 s[30:31], vcc
	global_load_dwordx4 v[222:225], v[230:231], off offset:1024
	s_mov_b64 exec, s[30:31]
	s_barrier
	s_waitcnt vmcnt(0)
	ds_write_b128 v226, v[206:209]
	ds_write_b128 v226, v[210:213] offset:8448
	ds_write_b128 v226, v[214:217] offset:16896
	ds_write_b128 v226, v[218:221] offset:25344
	ds_write_b128 v226, v[222:225] offset:33792
	v_cmp_gt_i32_e32 vcc, 64, v156
	s_and_saveexec_b64 s[30:31], vcc
	ds_write_b128 v233, v[196:199]
	s_mov_b64 exec, s[30:31]

.LBB0_403:
	s_andn2_b64 vcc, exec, s[0:1]
	s_cbranch_vccnz .LBB0_373
	s_mov_b64 s[28:29], -1
	s_cmp_eq_u32 s55, 1
	v_cmp_gt_i32_e64 s[0:1], 64, v156
	v_lshlrev_b32_e32 v0, 1, v157
	s_cbranch_scc1 .LBB0_415
	s_add_i32 s28, s48, s44
	s_ashr_i32 s29, s28, 31
	s_lshl_b64 s[28:29], s[28:29], 14
	s_add_u32 s28, s38, s28
	s_addc_u32 s29, s39, s29
	v_lshl_add_u64 v[10:11], s[28:29], 0, v[0:1]
	s_movk_i32 s23, 0x4000
	v_add_co_u32_e32 v12, vcc, s23, v10
	s_nop 1
	v_addc_co_u32_e32 v13, vcc, 0, v11, vcc
	global_load_dwordx4 v[2:5], v0, s[28:29]
	global_load_dwordx4 v[142:145], v0, s[28:29] offset:1024
	global_load_dwordx4 v[6:9], v[12:13], off
	global_load_dwordx4 v[146:149], v[12:13], off offset:1024
	global_load_dwordx4 v[138:141], v0, s[28:29] offset:2048
	global_load_dwordx4 v[122:125], v0, s[28:29] offset:3072
	global_load_dwordx4 v[150:153], v[12:13], off offset:2048
	global_load_dwordx4 v[126:129], v[12:13], off offset:3072
	v_add_co_u32_e32 v12, vcc, 0x1000, v10
	s_nop 1
	v_addc_co_u32_e32 v13, vcc, 0, v11, vcc
	v_add_co_u32_e32 v14, vcc, 0x5000, v10
	s_nop 1
	v_addc_co_u32_e32 v15, vcc, 0, v11, vcc
	global_load_dwordx4 v[130:133], v[12:13], off
	global_load_dwordx4 v[110:113], v[12:13], off offset:1024
	global_load_dwordx4 v[134:137], v[14:15], off
	global_load_dwordx4 v[114:117], v[14:15], off offset:1024
	global_load_dwordx4 v[106:109], v[12:13], off offset:2048
	global_load_dwordx4 v[90:93], v[12:13], off offset:3072
	global_load_dwordx4 v[118:121], v[14:15], off offset:2048
	global_load_dwordx4 v[94:97], v[14:15], off offset:3072
	v_add_co_u32_e32 v12, vcc, 0x2000, v10
	s_nop 1
	v_addc_co_u32_e32 v13, vcc, 0, v11, vcc
	v_add_co_u32_e32 v14, vcc, 0x6000, v10
	s_nop 1
	v_addc_co_u32_e32 v15, vcc, 0, v11, vcc
	global_load_dwordx4 v[98:101], v[12:13], off
	global_load_dwordx4 v[78:81], v[12:13], off offset:1024
	global_load_dwordx4 v[102:105], v[14:15], off
	global_load_dwordx4 v[82:85], v[14:15], off offset:1024
	global_load_dwordx4 v[74:77], v[12:13], off offset:2048
	global_load_dwordx4 v[58:61], v[12:13], off offset:3072
	global_load_dwordx4 v[86:89], v[14:15], off offset:2048
	global_load_dwordx4 v[62:65], v[14:15], off offset:3072
	v_add_co_u32_e32 v12, vcc, 0x3000, v10
	s_nop 1
	v_addc_co_u32_e32 v13, vcc, 0, v11, vcc
	v_add_co_u32_e32 v10, vcc, 0x7000, v10
	s_nop 1
	v_addc_co_u32_e32 v11, vcc, 0, v11, vcc
	global_load_dwordx4 v[66:69], v[12:13], off
	global_load_dwordx4 v[50:53], v[12:13], off offset:1024
	global_load_dwordx4 v[70:73], v[10:11], off
	global_load_dwordx4 v[54:57], v[10:11], off offset:1024
	global_load_dwordx4 v[46:49], v[12:13], off offset:2048
	global_load_dwordx4 v[38:41], v[12:13], off offset:3072
	global_load_dwordx4 v[42:45], v[10:11], off offset:2048
	global_load_dwordx4 v[34:37], v[10:11], off offset:3072
	s_and_saveexec_b64 s[28:29], s[0:1]
	s_cbranch_execz .LBB0_407
	v_lshlrev_b32_e32 v10, 2, v156
	v_ashrrev_i32_e32 v11, 31, v10
	v_lshl_add_u64 v[10:11], v[10:11], 2, s[40:41]
	global_load_dwordx4 v[196:199], v[10:11], off
	v_lshl_add_u32 v233, v156, 4, 0
	v_add_u32_e32 v233, 0x13000, v233
.LBB0_407:
	s_or_b64 exec, exec, s[28:29]
	s_movk_i32 s0, 0x840
	s_sub_i32 s55, s49, s54
	v_cmp_gt_i32_e32 vcc, s0, v156
	s_and_saveexec_b64 s[0:1], vcc
	s_cbranch_execz .LBB0_412
	v_lshlrev_b32_e32 v10, 4, v155
	v_mov_b32_e32 v11, v1
	s_add_i32 s23, s55, -1
	v_lshl_add_u64 v[14:15], s[24:25], 0, v[10:11]
	v_add_u32_e32 v16, 0, v10
	v_ashrrev_i32_e32 v227, 5, v156
	v_add_u32_e32 v228, s23, v227
	v_mad_u32_u24 v226, v227, s69, v16
	v_add_u32_e32 v232, s54, v228
	v_mad_i64_i32 v[230:231], s[62:63], v232, s77, v[14:15]
	v_mov_b32_e32 v206, 0
	v_mov_b32_e32 v207, 0
	v_mov_b32_e32 v208, 0
	v_mov_b32_e32 v209, 0
	v_cmp_gt_u32_e32 vcc, s51, v228
	s_and_saveexec_b64 s[30:31], vcc
	global_load_dwordx4 v[206:209], v[230:231], off
	s_mov_b64 exec, s[30:31]
	v_add_co_u32_e32 v230, vcc, 0x28000, v230
	s_nop 1
	v_addc_co_u32_e32 v231, vcc, 0, v231, vcc
	v_mov_b32_e32 v210, 0
	v_mov_b32_e32 v211, 0
	v_mov_b32_e32 v212, 0
	v_mov_b32_e32 v213, 0
	v_add_u32_e32 v229, 16, v228
	v_cmp_gt_u32_e32 vcc, s51, v229
	s_and_saveexec_b64 s[30:31], vcc
	global_load_dwordx4 v[210:213], v[230:231], off
	s_mov_b64 exec, s[30:31]
	v_add_co_u32_e32 v230, vcc, 0x28000, v230
	s_nop 1
	v_addc_co_u32_e32 v231, vcc, 0, v231, vcc
	v_mov_b32_e32 v214, 0
	v_mov_b32_e32 v215, 0
	v_mov_b32_e32 v216, 0
	v_mov_b32_e32 v217, 0
	v_add_u32_e32 v229, 32, v228
	v_cmp_gt_u32_e32 vcc, s51, v229
	s_and_saveexec_b64 s[30:31], vcc
	global_load_dwordx4 v[214:217], v[230:231], off
	s_mov_b64 exec, s[30:31]
	v_add_co_u32_e32 v230, vcc, 0x28000, v230
	s_nop 1
	v_addc_co_u32_e32 v231, vcc, 0, v231, vcc
	v_mov_b32_e32 v218, 0
	v_mov_b32_e32 v219, 0
	v_mov_b32_e32 v220, 0
	v_mov_b32_e32 v221, 0
	v_add_u32_e32 v229, 48, v228
	v_cmp_gt_u32_e32 vcc, s51, v229
	s_and_saveexec_b64 s[30:31], vcc
	global_load_dwordx4 v[218:221], v[230:231], off
	s_mov_b64 exec, s[30:31]
	v_add_co_u32_e32 v230, vcc, 0x28000, v230
	s_nop 1
	v_addc_co_u32_e32 v231, vcc, 0, v231, vcc
	v_mov_b32_e32 v222, 0
	v_mov_b32_e32 v223, 0
	v_mov_b32_e32 v224, 0
	v_mov_b32_e32 v225, 0
	v_add_u32_e32 v229, 64, v228
	v_cmp_gt_u32_e32 vcc, s51, v229
	s_and_saveexec_b64 s[30:31], vcc
	global_load_dwordx4 v[222:225], v[230:231], off
	s_mov_b64 exec, s[30:31]
	s_barrier
	s_waitcnt vmcnt(0)
	ds_write_b128 v226, v[206:209]
	ds_write_b128 v226, v[210:213] offset:8448
	ds_write_b128 v226, v[214:217] offset:16896
	ds_write_b128 v226, v[218:221] offset:25344
	ds_write_b128 v226, v[222:225] offset:33792
	v_cmp_gt_i32_e32 vcc, 64, v156
	s_and_saveexec_b64 s[30:31], vcc
	ds_write_b128 v233, v[196:199]
	s_mov_b64 exec, s[30:31]

.LBB0_415:
	s_and_b64 vcc, exec, s[28:29]
	s_cbranch_vccz .LBB0_373
	s_add_i32 s0, s47, s48
	s_ashr_i32 s1, s0, 31
	s_lshl_b64 s[0:1], s[0:1], 14
	s_add_u32 s0, s38, s0
	s_addc_u32 s1, s39, s1
	s_nop 3
	v_lshl_add_u64 v[10:11], s[0:1], 0, v[0:1]
	s_movk_i32 s23, 0x4000
	v_add_co_u32_e32 v12, vcc, s23, v10
	s_nop 1
	v_addc_co_u32_e32 v13, vcc, 0, v11, vcc
	global_load_dwordx4 v[2:5], v0, s[0:1]
	global_load_dwordx4 v[142:145], v0, s[0:1] offset:1024
	global_load_dwordx4 v[6:9], v[12:13], off
	global_load_dwordx4 v[146:149], v[12:13], off offset:1024
	global_load_dwordx4 v[138:141], v0, s[0:1] offset:2048
	global_load_dwordx4 v[122:125], v0, s[0:1] offset:3072
	global_load_dwordx4 v[150:153], v[12:13], off offset:2048
	global_load_dwordx4 v[126:129], v[12:13], off offset:3072
	v_add_co_u32_e32 v12, vcc, 0x1000, v10
	s_nop 1
	v_addc_co_u32_e32 v13, vcc, 0, v11, vcc
	v_add_co_u32_e32 v14, vcc, 0x5000, v10
	s_nop 1
	v_addc_co_u32_e32 v15, vcc, 0, v11, vcc
	global_load_dwordx4 v[130:133], v[12:13], off
	global_load_dwordx4 v[110:113], v[12:13], off offset:1024
	global_load_dwordx4 v[134:137], v[14:15], off
	global_load_dwordx4 v[114:117], v[14:15], off offset:1024
	global_load_dwordx4 v[106:109], v[12:13], off offset:2048
	global_load_dwordx4 v[90:93], v[12:13], off offset:3072
	global_load_dwordx4 v[118:121], v[14:15], off offset:2048
	global_load_dwordx4 v[94:97], v[14:15], off offset:3072
	v_add_co_u32_e32 v12, vcc, 0x2000, v10
	s_nop 1
	v_addc_co_u32_e32 v13, vcc, 0, v11, vcc
	v_add_co_u32_e32 v14, vcc, 0x6000, v10
	s_nop 1
	v_addc_co_u32_e32 v15, vcc, 0, v11, vcc
	global_load_dwordx4 v[98:101], v[12:13], off
	global_load_dwordx4 v[78:81], v[12:13], off offset:1024
	global_load_dwordx4 v[102:105], v[14:15], off
	global_load_dwordx4 v[82:85], v[14:15], off offset:1024
	global_load_dwordx4 v[74:77], v[12:13], off offset:2048
	global_load_dwordx4 v[58:61], v[12:13], off offset:3072
	global_load_dwordx4 v[86:89], v[14:15], off offset:2048
	global_load_dwordx4 v[62:65], v[14:15], off offset:3072
	v_add_co_u32_e32 v12, vcc, 0x3000, v10
	s_nop 1
	v_addc_co_u32_e32 v13, vcc, 0, v11, vcc
	v_add_co_u32_e32 v10, vcc, 0x7000, v10
	s_nop 1
	v_addc_co_u32_e32 v11, vcc, 0, v11, vcc
	global_load_dwordx4 v[66:69], v[12:13], off
	global_load_dwordx4 v[46:49], v[12:13], off offset:1024
	global_load_dwordx4 v[70:73], v[10:11], off
	global_load_dwordx4 v[50:53], v[10:11], off offset:1024
	global_load_dwordx4 v[42:45], v[12:13], off offset:2048
	global_load_dwordx4 v[38:41], v[12:13], off offset:3072
	global_load_dwordx4 v[54:57], v[10:11], off offset:2048
	global_load_dwordx4 v[34:37], v[10:11], off offset:3072
	v_cmp_gt_i32_e32 vcc, 64, v156
	s_and_saveexec_b64 s[0:1], vcc
	s_cbranch_execz .LBB0_418
	v_lshlrev_b32_e32 v10, 2, v156
	v_ashrrev_i32_e32 v11, 31, v10
	v_lshl_add_u64 v[10:11], v[10:11], 2, s[40:41]
	global_load_dwordx4 v[196:199], v[10:11], off offset:1024
	v_lshl_add_u32 v233, v156, 4, 0
	v_add_u32_e32 v233, 0x13000, v233
.LBB0_418:
	s_or_b64 exec, exec, s[0:1]
	s_movk_i32 s0, 0x880
	s_sub_i32 s55, s49, s54
	v_cmp_gt_i32_e32 vcc, s0, v156
	s_and_saveexec_b64 s[0:1], vcc
	s_cbranch_execz .LBB0_423
	v_lshlrev_b32_e32 v0, 4, v155
	s_add_i32 s23, s55, -2
	v_add_u32_e32 v14, 0, v0
	v_lshl_add_u64 v[16:17], s[24:25], 0, v[0:1]
	v_ashrrev_i32_e32 v227, 5, v156
	v_add_u32_e32 v228, s23, v227
	v_mad_u32_u24 v226, v227, s69, v14
	v_add_u32_e32 v232, s54, v228
	v_mad_i64_i32 v[230:231], s[62:63], v232, s77, v[16:17]
	v_mov_b32_e32 v206, 0
	v_mov_b32_e32 v207, 0
	v_mov_b32_e32 v208, 0
	v_mov_b32_e32 v209, 0
	v_cmp_gt_u32_e32 vcc, s51, v228
	s_and_saveexec_b64 s[30:31], vcc
	global_load_dwordx4 v[206:209], v[230:231], off offset:512
	s_mov_b64 exec, s[30:31]
	v_add_co_u32_e32 v230, vcc, 0x28000, v230
	s_nop 1
	v_addc_co_u32_e32 v231, vcc, 0, v231, vcc
	v_mov_b32_e32 v210, 0
	v_mov_b32_e32 v211, 0
	v_mov_b32_e32 v212, 0
	v_mov_b32_e32 v213, 0
	v_add_u32_e32 v229, 16, v228
	v_cmp_gt_u32_e32 vcc, s51, v229
	s_and_saveexec_b64 s[30:31], vcc
	global_load_dwordx4 v[210:213], v[230:231], off offset:512
	s_mov_b64 exec, s[30:31]
	v_add_co_u32_e32 v230, vcc, 0x28000, v230
	s_nop 1
	v_addc_co_u32_e32 v231, vcc, 0, v231, vcc
	v_mov_b32_e32 v214, 0
	v_mov_b32_e32 v215, 0
	v_mov_b32_e32 v216, 0
	v_mov_b32_e32 v217, 0
	v_add_u32_e32 v229, 32, v228
	v_cmp_gt_u32_e32 vcc, s51, v229
	s_and_saveexec_b64 s[30:31], vcc
	global_load_dwordx4 v[214:217], v[230:231], off offset:512
	s_mov_b64 exec, s[30:31]
	v_add_co_u32_e32 v230, vcc, 0x28000, v230
	s_nop 1
	v_addc_co_u32_e32 v231, vcc, 0, v231, vcc
	v_mov_b32_e32 v218, 0
	v_mov_b32_e32 v219, 0
	v_mov_b32_e32 v220, 0
	v_mov_b32_e32 v221, 0
	v_add_u32_e32 v229, 48, v228
	v_cmp_gt_u32_e32 vcc, s51, v229
	s_and_saveexec_b64 s[30:31], vcc
	global_load_dwordx4 v[218:221], v[230:231], off offset:512
	s_mov_b64 exec, s[30:31]
	v_add_co_u32_e32 v230, vcc, 0x28000, v230
	s_nop 1
	v_addc_co_u32_e32 v231, vcc, 0, v231, vcc
	v_mov_b32_e32 v222, 0
	v_mov_b32_e32 v223, 0
	v_mov_b32_e32 v224, 0
	v_mov_b32_e32 v225, 0
	v_add_u32_e32 v229, 64, v228
	v_cmp_gt_u32_e32 vcc, s51, v229
	s_and_saveexec_b64 s[30:31], vcc
	global_load_dwordx4 v[222:225], v[230:231], off offset:512
	s_mov_b64 exec, s[30:31]
	s_barrier
	s_waitcnt vmcnt(0)
	ds_write_b128 v226, v[206:209]
	ds_write_b128 v226, v[210:213] offset:8448
	ds_write_b128 v226, v[214:217] offset:16896
	ds_write_b128 v226, v[218:221] offset:25344
	ds_write_b128 v226, v[222:225] offset:33792
	v_cmp_gt_i32_e32 vcc, 64, v156
	s_and_saveexec_b64 s[30:31], vcc
	ds_write_b128 v233, v[196:199]
	s_mov_b64 exec, s[30:31]
